# plus B/C/D: deferred-max threshold test on per-lane partial row max; cross-half permlane swap + max only on the rare rescale path
# speedup vs baseline: 1.0082x; 1.0082x over previous
; __device__ __forceinline__ void qkt12_roll(f32x16& p0, f32x16& p1, const f32x16& negm, int kb, int qa, const bf16x8* qr) {
;   const int a0 = kb ^ (0 << 5); const bf16x8 x0 = lds_rd128<0>(a0), y0 = lds_rd128<12288>(a0);
;   const int a1 = kb ^ (1 << 5); const bf16x8 x1 = lds_rd128<0>(a1), y1 = lds_rd128<12288>(a1);
;   asm volatile("s_waitcnt lgkmcnt(2)" ::: "memory"); SBAR();
;   p0 = __builtin_amdgcn_mfma_f32_32x32x16_bf16(x0, qr[0], negm, 0, 0, 0); p1 = __builtin_amdgcn_mfma_f32_32x32x16_bf16(y0, qr[0], negm, 0, 0, 0);
;   const int a2 = kb ^ (2 << 5); const bf16x8 x2 = lds_rd128<0>(a2), y2 = lds_rd128<12288>(a2);
;   asm volatile("s_waitcnt lgkmcnt(2)" ::: "memory"); SBAR();
;   p0 = __builtin_amdgcn_mfma_f32_32x32x16_bf16(x1, qr[1], p0, 0, 0, 0); p1 = __builtin_amdgcn_mfma_f32_32x32x16_bf16(y1, qr[1], p1, 0, 0, 0);
;   const int a3 = kb ^ (3 << 5); const bf16x8 x3 = lds_rd128<0>(a3), y3 = lds_rd128<12288>(a3);
;   asm volatile("s_waitcnt lgkmcnt(2)" ::: "memory"); SBAR();
;   p0 = __builtin_amdgcn_mfma_f32_32x32x16_bf16(x2, qr[2], p0, 0, 0, 0); p1 = __builtin_amdgcn_mfma_f32_32x32x16_bf16(y2, qr[2], p1, 0, 0, 0);
;   const int a4 = kb ^ (0 << 5); const bf16x8 x4 = lds_rd128<128>(a4), y4 = lds_rd128<12416>(a4);
;   asm volatile("s_waitcnt lgkmcnt(2)" ::: "memory"); SBAR();
;   p0 = __builtin_amdgcn_mfma_f32_32x32x16_bf16(x3, qr[3], p0, 0, 0, 0); p1 = __builtin_amdgcn_mfma_f32_32x32x16_bf16(y3, qr[3], p1, 0, 0, 0);
;   const int a5 = kb ^ (1 << 5); const bf16x8 x5 = lds_rd128<128>(a5), y5 = lds_rd128<12416>(a5);
;   asm volatile("s_waitcnt lgkmcnt(2)" ::: "memory"); SBAR();
;   p0 = __builtin_amdgcn_mfma_f32_32x32x16_bf16(x4, qr[4], p0, 0, 0, 0); p1 = __builtin_amdgcn_mfma_f32_32x32x16_bf16(y4, qr[4], p1, 0, 0, 0);
;   const int a6 = kb ^ (2 << 5); const bf16x8 x6 = lds_rd128<128>(a6), y6 = lds_rd128<12416>(a6);
;   asm volatile("s_waitcnt lgkmcnt(2)" ::: "memory"); SBAR();
;   p0 = __builtin_amdgcn_mfma_f32_32x32x16_bf16(x5, qr[5], p0, 0, 0, 0); p1 = __builtin_amdgcn_mfma_f32_32x32x16_bf16(y5, qr[5], p1, 0, 0, 0);
;   const int a7 = kb ^ (3 << 5); const bf16x8 x7 = lds_rd128<128>(a7), y7 = lds_rd128<12416>(a7);
;   asm volatile("s_waitcnt lgkmcnt(2)" ::: "memory"); SBAR();
;   p0 = __builtin_amdgcn_mfma_f32_32x32x16_bf16(x6, qr[6], p0, 0, 0, 0); p1 = __builtin_amdgcn_mfma_f32_32x32x16_bf16(y6, qr[6], p1, 0, 0, 0);
.LBB0_360:
	v_exp_f32_e32 v66, v66
	v_exp_f32_e32 v67, v67
	v_exp_f32_e32 v68, v68
	v_exp_f32_e32 v69, v69
	v_exp_f32_e32 v70, v70
	v_exp_f32_e32 v71, v71
	v_exp_f32_e32 v72, v72
	v_exp_f32_e32 v73, v73
	v_add_f32_e32 v98, v148, v146
	v_add_f32_e32 v99, v159, v161
	v_add_f32_e32 v100, v149, v147
	v_add_f32_e32 v101, v158, v160
	v_exp_f32_e32 v74, v74
	v_exp_f32_e32 v75, v75
	v_exp_f32_e32 v76, v76
	v_exp_f32_e32 v77, v77
	v_add_f32_e32 v98, v150, v98
	v_add_f32_e32 v99, v157, v99
	v_add_f32_e32 v100, v151, v100
	v_add_f32_e32 v101, v156, v101
	v_exp_f32_e32 v78, v78
	v_exp_f32_e32 v79, v79
	v_exp_f32_e32 v80, v80
	v_exp_f32_e32 v81, v81
	v_add_f32_e32 v98, v152, v98
	v_add_f32_e32 v99, v155, v99
	v_add_f32_e32 v100, v153, v100
	v_add_f32_e32 v101, v154, v101
	v_add_f32_e32 v98, v66, v98
	v_add_f32_e32 v99, v67, v99
	v_add_f32_e32 v100, v68, v100
	v_add_f32_e32 v101, v69, v101
	v_add_f32_e32 v98, v70, v98
	v_add_f32_e32 v99, v71, v99
	v_add_f32_e32 v100, v72, v100
	v_add_f32_e32 v101, v73, v101
	v_add_f32_e32 v98, v74, v98
	v_add_f32_e32 v99, v75, v99
	v_add_f32_e32 v100, v76, v100
	v_add_f32_e32 v101, v77, v101
	v_add_f32_e32 v98, v78, v98
	v_add_f32_e32 v99, v79, v99
	v_add_f32_e32 v100, v80, v100
	v_add_f32_e32 v101, v81, v101
	v_add_f32_e32 v98, v98, v99
	v_add_f32_e32 v99, v100, v101
	v_add_f32_e32 v224, v98, v99
	v_mov_b32_e32 v225, v224
	v_cvt_pk_bf16_f32 v146, v146, v161
	v_cvt_pk_bf16_f32 v147, v147, v160
	v_cvt_pk_bf16_f32 v148, v148, v159
	v_cvt_pk_bf16_f32 v149, v149, v158
	v_cvt_pk_bf16_f32 v150, v150, v157
	v_cvt_pk_bf16_f32 v151, v151, v156
	v_cvt_pk_bf16_f32 v152, v152, v155
	v_cvt_pk_bf16_f32 v153, v153, v154
	v_cvt_pk_bf16_f32 v158, v66, v67
	v_cvt_pk_bf16_f32 v159, v68, v69
	v_cvt_pk_bf16_f32 v160, v70, v71
	v_cvt_pk_bf16_f32 v161, v72, v73
	v_cvt_pk_bf16_f32 v154, v74, v75
	v_cvt_pk_bf16_f32 v155, v76, v77
	v_cvt_pk_bf16_f32 v156, v78, v79
	v_cvt_pk_bf16_f32 v157, v80, v81
	s_nop 1
	v_permlane32_swap_b32_e32 v224, v225
	v_cmp_neq_f32_e64 s[6:7], v229, -v226
	s_cmp_eq_u64 s[6:7], 0
	s_cselect_b64 s[6:7], -1, 0
	v_cndmask_b32_e64 v81, -v226, v97, s[6:7]
	v_cndmask_b32_e64 v80, -v226, v96, s[6:7]
	v_cndmask_b32_e64 v79, -v226, v95, s[6:7]
	v_cndmask_b32_e64 v78, -v226, v94, s[6:7]
	v_cndmask_b32_e64 v77, -v226, v93, s[6:7]
	v_cndmask_b32_e64 v76, -v226, v92, s[6:7]
	v_cndmask_b32_e64 v75, -v226, v91, s[6:7]
	v_cndmask_b32_e64 v74, -v226, v90, s[6:7]
	v_cndmask_b32_e64 v73, -v226, v89, s[6:7]
	v_cndmask_b32_e64 v72, -v226, v88, s[6:7]
	v_cndmask_b32_e64 v71, -v226, v87, s[6:7]
	v_cndmask_b32_e64 v70, -v226, v86, s[6:7]
	v_cndmask_b32_e64 v69, -v226, v85, s[6:7]
	v_cndmask_b32_e64 v68, -v226, v84, s[6:7]
	v_cndmask_b32_e64 v67, -v226, v83, s[6:7]
	v_cndmask_b32_e64 v66, -v226, v82, s[6:7]
	ds_read_b128 v[82:85], v221 offset:0
	ds_read_b128 v[162:165], v221 offset:0x3000
	ds_read_b128 v[166:169], v220 offset:0
	ds_read_b128 v[170:173], v220 offset:0x3000
	s_waitcnt lgkmcnt(2)
	s_nop 1
	v_mfma_f32_32x32x16_bf16 v[98:113], v[82:85], v[142:145], v[66:81]
	v_mfma_f32_32x32x16_bf16 v[82:97], v[162:165], v[142:145], v[66:81]
	ds_read_b128 v[162:165], v219 offset:0
	ds_read_b128 v[174:177], v219 offset:0x3000
	s_waitcnt lgkmcnt(2)
	v_mfma_f32_32x32x16_bf16 v[98:113], v[166:169], v[138:141], v[98:113]
	ds_read_b128 v[166:169], v218 offset:0
	v_mfma_f32_32x32x16_bf16 v[82:97], v[170:173], v[138:141], v[82:97]
	ds_read_b128 v[170:173], v218 offset:0x3000
	s_waitcnt lgkmcnt(2)
	v_mfma_f32_32x32x16_bf16 v[98:113], v[162:165], v[134:137], v[98:113]
	ds_read_b128 v[162:165], v221 offset:0x80
	v_mfma_f32_32x32x16_bf16 v[82:97], v[174:177], v[134:137], v[82:97]
	ds_read_b128 v[174:177], v221 offset:0x3080
	s_waitcnt lgkmcnt(2)
	v_mfma_f32_32x32x16_bf16 v[98:113], v[166:169], v[130:133], v[98:113]
	ds_read_b128 v[166:169], v220 offset:0x80
	v_mfma_f32_32x32x16_bf16 v[82:97], v[170:173], v[130:133], v[82:97]
	ds_read_b128 v[170:173], v220 offset:0x3080
	s_waitcnt lgkmcnt(2)
	v_mfma_f32_32x32x16_bf16 v[98:113], v[162:165], v[126:129], v[98:113]
	ds_read_b128 v[162:165], v219 offset:0x80
	v_mfma_f32_32x32x16_bf16 v[82:97], v[174:177], v[126:129], v[82:97]
	ds_read_b128 v[174:177], v219 offset:0x3080
	s_waitcnt lgkmcnt(2)
	v_mfma_f32_32x32x16_bf16 v[98:113], v[166:169], v[122:125], v[98:113]
	ds_read_b128 v[166:169], v218 offset:0x80
	v_mfma_f32_32x32x16_bf16 v[82:97], v[170:173], v[122:125], v[82:97]
	ds_read_b128 v[170:173], v218 offset:0x3080
	s_waitcnt lgkmcnt(2)
	v_mfma_f32_32x32x16_bf16 v[98:113], v[162:165], v[118:121], v[98:113]
	ds_read_b128 v[162:165], v221 offset:0x100
	v_mfma_f32_32x32x16_bf16 v[82:97], v[174:177], v[118:121], v[82:97]
	ds_read_b128 v[174:177], v221 offset:0x3100
	ds_read_b128 v[178:181], v199 offset:0
	s_waitcnt lgkmcnt(3)
	v_mfma_f32_32x32x16_bf16 v[98:113], v[166:169], v[114:117], v[98:113]
	ds_read_b128 v[166:169], v220 offset:0x100
	v_mfma_f32_32x32x16_bf16 v[82:97], v[170:173], v[114:117], v[82:97]
	ds_read_b128 v[170:173], v220 offset:0x3100
	ds_read_b128 v[230:233], v199 offset:0x400
	s_waitcnt lgkmcnt(3)
	v_mfma_f32_32x32x16_bf16 v[98:113], v[162:165], v[178:181], v[98:113]
	ds_read_b128 v[162:165], v219 offset:0x100
	v_mfma_f32_32x32x16_bf16 v[82:97], v[174:177], v[178:181], v[82:97]
	ds_read_b128 v[174:177], v219 offset:0x3100
	ds_read_b128 v[178:181], v199 offset:0x800
	s_waitcnt lgkmcnt(3)
	v_mfma_f32_32x32x16_bf16 v[98:113], v[166:169], v[230:233], v[98:113]
	ds_read_b128 v[166:169], v218 offset:0x100
	v_mfma_f32_32x32x16_bf16 v[82:97], v[170:173], v[230:233], v[82:97]
	ds_read_b128 v[170:173], v218 offset:0x3100
	ds_read_b128 v[230:233], v199 offset:0xc00
	s_waitcnt lgkmcnt(3)
	v_mfma_f32_32x32x16_bf16 v[98:113], v[162:165], v[178:181], v[98:113]
	s_waitcnt lgkmcnt(0)
	v_mfma_f32_32x32x16_bf16 v[82:97], v[174:177], v[178:181], v[82:97]
	v_mfma_f32_32x32x16_bf16 v[98:113], v[166:169], v[230:233], v[98:113]
	v_mfma_f32_32x32x16_bf16 v[82:97], v[170:173], v[230:233], v[82:97]
	s_nop 10
	v_max_f32_e32 v162, v98, v102
	v_max_f32_e32 v163, v99, v103
	v_max_f32_e32 v164, v101, v105
	v_max3_f32 v165, v100, v104, v108
	v_max3_f32 v164, v164, v109, v113
	v_max3_f32 v162, v162, v106, v110
	v_max3_f32 v163, v163, v107, v111
	v_max3_f32 v165, v165, v112, v84
	v_max3_f32 v164, v164, v85, v89
	v_max3_f32 v162, v162, v82, v86
	v_max3_f32 v163, v163, v83, v87
	v_max3_f32 v165, v165, v88, v92
	v_max3_f32 v164, v164, v93, v97
	v_max3_f32 v162, v162, v90, v94
	v_max3_f32 v163, v163, v91, v95
	v_max3_f32 v164, v165, v96, v164
	v_max3_f32 v162, v162, v163, v164
	v_cmp_ge_f32_e32 vcc, s48, v162
	s_cmp_eq_u64 vcc, exec
	s_cbranch_scc0 .LBB0_374
	v_mov_b32_e32 v228, v226
	v_mov_b32_e32 v227, 1.0

; template <bool FIRST>
; __device__ __forceinline__ void partialSM(f32x16& p0, f32x16& p1, float& mC, float& alpha) {
;     ...
;   for (int r = 0; r < 16; ++r) p0[r] = __builtin_amdgcn_exp2f(p0[r]);
; }
; template <bool EXP1 = true>
; __device__ __forceinline__ void finishSM(f32x16& p0, f32x16& p1, float alpha, float& l_reg, bf16x8& pa0, bf16x8& pa1, bf16x8& pa2, bf16x8& pa3) {
;   if constexpr (EXP1) {
; #pragma unroll
;   for (int r = 0; r < 16; ++r) p1[r] = __builtin_amdgcn_exp2f(p1[r]);
;   }
;   float sm_[4] = {p0[0], p0[1], p0[2], p0[3]};
; #pragma unroll
;   for (int r = 4; r < 16; ++r) sm_[r & 3] += p0[r];
; #pragma unroll
;   for (int r = 0; r < 16; ++r) sm_[r & 3] += p1[r];
;   float ps = (sm_[0] + sm_[1]) + (sm_[2] + sm_[3]);
;   { auto rr = __builtin_amdgcn_permlane32_swap(__float_as_uint(ps), __float_as_uint(ps), false, false);
;     ps = __uint_as_float(rr[0]) + __uint_as_float(rr[1]); }
;   l_reg = l_reg * alpha + ps;
.LBB0_366:
	v_exp_f32_e32 v146, v98
	v_exp_f32_e32 v153, v99
	v_exp_f32_e32 v147, v100
	v_exp_f32_e32 v152, v101
	v_exp_f32_e32 v148, v102
	v_exp_f32_e32 v151, v103
	v_exp_f32_e32 v149, v104
	v_exp_f32_e32 v150, v105
	v_exp_f32_e32 v103, v106
	v_exp_f32_e32 v105, v107
	v_exp_f32_e32 v101, v108
	v_exp_f32_e32 v104, v109
	v_exp_f32_e32 v99, v110
	v_exp_f32_e32 v102, v111
	v_exp_f32_e32 v98, v112
	v_exp_f32_e32 v100, v113
	v_xor_b32_e32 v106, 0x80000000, v226
	v_exp_f32_e32 v82, v82
	v_exp_f32_e32 v83, v83
	v_exp_f32_e32 v84, v84
	v_exp_f32_e32 v85, v85
	v_cndmask_b32_e64 v229, v106, v229, s[6:7]
	v_exp_f32_e32 v86, v86
	v_exp_f32_e32 v87, v87
	v_exp_f32_e32 v88, v88
	v_exp_f32_e32 v89, v89
	v_add_f32_e32 v106, v148, v146
	v_add_f32_e32 v107, v151, v153
	v_add_f32_e32 v108, v149, v147
	v_add_f32_e32 v109, v150, v152
	v_exp_f32_e32 v90, v90
	v_exp_f32_e32 v91, v91
	v_exp_f32_e32 v92, v92
	v_exp_f32_e32 v93, v93
	v_add_f32_e32 v106, v103, v106
	v_add_f32_e32 v107, v105, v107
	v_add_f32_e32 v108, v101, v108
	v_add_f32_e32 v109, v104, v109
	v_exp_f32_e32 v94, v94
	v_exp_f32_e32 v95, v95
	v_exp_f32_e32 v96, v96
	v_exp_f32_e32 v97, v97
	v_add_f32_e32 v106, v99, v106
	v_add_f32_e32 v107, v102, v107
	v_add_f32_e32 v108, v98, v108
	v_add_f32_e32 v109, v100, v109
	v_add_f32_e32 v106, v82, v106
	v_add_f32_e32 v107, v107, v83
	v_add_f32_e32 v108, v108, v84
	v_add_f32_e32 v109, v109, v85
	v_add_f32_e32 v106, v86, v106
	v_add_f32_e32 v107, v87, v107
	v_add_f32_e32 v108, v88, v108
	v_add_f32_e32 v109, v89, v109
	v_add_f32_e32 v106, v90, v106
	v_add_f32_e32 v107, v91, v107
	v_add_f32_e32 v108, v92, v108
	v_add_f32_e32 v109, v93, v109
	v_add_f32_e32 v106, v94, v106
	v_add_f32_e32 v107, v95, v107
	v_add_f32_e32 v108, v96, v108
	v_add_f32_e32 v109, v97, v109
	v_add_f32_e32 v106, v106, v107
	v_add_f32_e32 v107, v108, v109
	v_add_f32_e32 v230, v106, v107
	s_waitcnt lgkmcnt(0)
	s_barrier
; __device__ __forceinline__ void qkt12_roll(f32x16& p0, f32x16& p1, const f32x16& negm, int kb, int qa, const bf16x8* qr) {
;   const int a0 = kb ^ (0 << 5); const bf16x8 x0 = lds_rd128<0>(a0), y0 = lds_rd128<12288>(a0);
;   const int a1 = kb ^ (1 << 5); const bf16x8 x1 = lds_rd128<0>(a1), y1 = lds_rd128<12288>(a1);
;   asm volatile("s_waitcnt lgkmcnt(2)" ::: "memory"); SBAR();
;   p0 = __builtin_amdgcn_mfma_f32_32x32x16_bf16(x0, qr[0], negm, 0, 0, 0); p1 = __builtin_amdgcn_mfma_f32_32x32x16_bf16(y0, qr[0], negm, 0, 0, 0);
;   const int a2 = kb ^ (2 << 5); const bf16x8 x2 = lds_rd128<0>(a2), y2 = lds_rd128<12288>(a2);
;   asm volatile("s_waitcnt lgkmcnt(2)" ::: "memory"); SBAR();
;   p0 = __builtin_amdgcn_mfma_f32_32x32x16_bf16(x1, qr[1], p0, 0, 0, 0); p1 = __builtin_amdgcn_mfma_f32_32x32x16_bf16(y1, qr[1], p1, 0, 0, 0);
;   const int a3 = kb ^ (3 << 5); const bf16x8 x3 = lds_rd128<0>(a3), y3 = lds_rd128<12288>(a3);
;   asm volatile("s_waitcnt lgkmcnt(2)" ::: "memory"); SBAR();
;   p0 = __builtin_amdgcn_mfma_f32_32x32x16_bf16(x2, qr[2], p0, 0, 0, 0); p1 = __builtin_amdgcn_mfma_f32_32x32x16_bf16(y2, qr[2], p1, 0, 0, 0);
;   const int a4 = kb ^ (0 << 5); const bf16x8 x4 = lds_rd128<128>(a4), y4 = lds_rd128<12416>(a4);
;   asm volatile("s_waitcnt lgkmcnt(2)" ::: "memory"); SBAR();
;   p0 = __builtin_amdgcn_mfma_f32_32x32x16_bf16(x3, qr[3], p0, 0, 0, 0); p1 = __builtin_amdgcn_mfma_f32_32x32x16_bf16(y3, qr[3], p1, 0, 0, 0);
;   const int a5 = kb ^ (1 << 5); const bf16x8 x5 = lds_rd128<128>(a5), y5 = lds_rd128<12416>(a5);
;   asm volatile("s_waitcnt lgkmcnt(2)" ::: "memory"); SBAR();
;   p0 = __builtin_amdgcn_mfma_f32_32x32x16_bf16(x4, qr[4], p0, 0, 0, 0); p1 = __builtin_amdgcn_mfma_f32_32x32x16_bf16(y4, qr[4], p1, 0, 0, 0);
;   const int a6 = kb ^ (2 << 5); const bf16x8 x6 = lds_rd128<128>(a6), y6 = lds_rd128<12416>(a6);
;   asm volatile("s_waitcnt lgkmcnt(2)" ::: "memory"); SBAR();
;   p0 = __builtin_amdgcn_mfma_f32_32x32x16_bf16(x5, qr[5], p0, 0, 0, 0); p1 = __builtin_amdgcn_mfma_f32_32x32x16_bf16(y5, qr[5], p1, 0, 0, 0);
;   const int a7 = kb ^ (3 << 5); const bf16x8 x7 = lds_rd128<128>(a7), y7 = lds_rd128<12416>(a7);
;   asm volatile("s_waitcnt lgkmcnt(2)" ::: "memory"); SBAR();
;   p0 = __builtin_amdgcn_mfma_f32_32x32x16_bf16(x6, qr[6], p0, 0, 0, 0); p1 = __builtin_amdgcn_mfma_f32_32x32x16_bf16(y6, qr[6], p1, 0, 0, 0);
	v_mov_b32_e32 v231, v230
	v_cvt_pk_bf16_f32 v146, v146, v153
	v_cvt_pk_bf16_f32 v147, v147, v152
	v_cvt_pk_bf16_f32 v148, v148, v151
	v_cvt_pk_bf16_f32 v149, v149, v150
	v_cvt_pk_bf16_f32 v150, v103, v105
	v_cvt_pk_bf16_f32 v151, v101, v104
	v_cvt_pk_bf16_f32 v152, v99, v102
	v_cvt_pk_bf16_f32 v153, v98, v100
	v_cvt_pk_bf16_f32 v158, v82, v83
	v_cvt_pk_bf16_f32 v159, v84, v85
	v_cvt_pk_bf16_f32 v160, v86, v87
	v_cvt_pk_bf16_f32 v161, v88, v89
	v_cvt_pk_bf16_f32 v154, v90, v91
	v_cvt_pk_bf16_f32 v155, v92, v93
	v_cvt_pk_bf16_f32 v156, v94, v95
	v_cvt_pk_bf16_f32 v157, v96, v97
	s_nop 1
	v_permlane32_swap_b32_e32 v230, v231
	v_cmp_neq_f32_e64 s[6:7], v229, -v228
	s_cmp_eq_u64 s[6:7], 0
	s_cselect_b64 s[6:7], -1, 0
	v_cndmask_b32_e64 v97, -v228, v81, s[6:7]
	v_cndmask_b32_e64 v96, -v228, v80, s[6:7]
	v_cndmask_b32_e64 v95, -v228, v79, s[6:7]
	v_cndmask_b32_e64 v94, -v228, v78, s[6:7]
	v_cndmask_b32_e64 v93, -v228, v77, s[6:7]
	v_cndmask_b32_e64 v92, -v228, v76, s[6:7]
	v_cndmask_b32_e64 v91, -v228, v75, s[6:7]
	v_cndmask_b32_e64 v90, -v228, v74, s[6:7]
	v_cndmask_b32_e64 v89, -v228, v73, s[6:7]
	v_cndmask_b32_e64 v88, -v228, v72, s[6:7]
	v_cndmask_b32_e64 v87, -v228, v71, s[6:7]
	v_cndmask_b32_e64 v86, -v228, v70, s[6:7]
	v_cndmask_b32_e64 v85, -v228, v69, s[6:7]
	v_cndmask_b32_e64 v84, -v228, v68, s[6:7]
	v_cndmask_b32_e64 v83, -v228, v67, s[6:7]
	v_cndmask_b32_e64 v82, -v228, v66, s[6:7]
	ds_read_b128 v[66:69], v209 offset:0
	ds_read_b128 v[162:165], v209 offset:0x3000
	ds_read_b128 v[166:169], v215 offset:0
	ds_read_b128 v[170:173], v215 offset:0x3000
	s_waitcnt lgkmcnt(2)
	s_nop 1
	v_mfma_f32_32x32x16_bf16 v[98:113], v[66:69], v[142:145], v[82:97]
	v_mfma_f32_32x32x16_bf16 v[66:81], v[162:165], v[142:145], v[82:97]
	ds_read_b128 v[162:165], v216 offset:0
	ds_read_b128 v[174:177], v216 offset:0x3000
	s_waitcnt lgkmcnt(2)
	v_mfma_f32_32x32x16_bf16 v[98:113], v[166:169], v[138:141], v[98:113]
	ds_read_b128 v[166:169], v217 offset:0
	v_mfma_f32_32x32x16_bf16 v[66:81], v[170:173], v[138:141], v[66:81]
	ds_read_b128 v[170:173], v217 offset:0x3000
	s_waitcnt lgkmcnt(2)
	v_mfma_f32_32x32x16_bf16 v[98:113], v[162:165], v[134:137], v[98:113]
	ds_read_b128 v[162:165], v209 offset:0x80
	v_mfma_f32_32x32x16_bf16 v[66:81], v[174:177], v[134:137], v[66:81]
	ds_read_b128 v[174:177], v209 offset:0x3080
	s_waitcnt lgkmcnt(2)
	v_mfma_f32_32x32x16_bf16 v[98:113], v[166:169], v[130:133], v[98:113]
	ds_read_b128 v[166:169], v215 offset:0x80
	v_mfma_f32_32x32x16_bf16 v[66:81], v[170:173], v[130:133], v[66:81]
	ds_read_b128 v[170:173], v215 offset:0x3080
	s_waitcnt lgkmcnt(2)
	v_mfma_f32_32x32x16_bf16 v[98:113], v[162:165], v[126:129], v[98:113]
	ds_read_b128 v[162:165], v216 offset:0x80
	v_mfma_f32_32x32x16_bf16 v[66:81], v[174:177], v[126:129], v[66:81]
	ds_read_b128 v[174:177], v216 offset:0x3080
	s_waitcnt lgkmcnt(2)
	v_mfma_f32_32x32x16_bf16 v[98:113], v[166:169], v[122:125], v[98:113]
	ds_read_b128 v[166:169], v217 offset:0x80
	v_mfma_f32_32x32x16_bf16 v[66:81], v[170:173], v[122:125], v[66:81]
	ds_read_b128 v[170:173], v217 offset:0x3080
	s_waitcnt lgkmcnt(2)
	v_mfma_f32_32x32x16_bf16 v[98:113], v[162:165], v[118:121], v[98:113]
	ds_read_b128 v[162:165], v209 offset:0x100
	v_mfma_f32_32x32x16_bf16 v[66:81], v[174:177], v[118:121], v[66:81]
	ds_read_b128 v[174:177], v209 offset:0x3100
	ds_read_b128 v[178:181], v199 offset:0
	s_waitcnt lgkmcnt(3)
	v_mfma_f32_32x32x16_bf16 v[98:113], v[166:169], v[114:117], v[98:113]
	ds_read_b128 v[166:169], v215 offset:0x100
	v_mfma_f32_32x32x16_bf16 v[66:81], v[170:173], v[114:117], v[66:81]
	ds_read_b128 v[170:173], v215 offset:0x3100
	ds_read_b128 v[232:235], v199 offset:0x400
	s_waitcnt lgkmcnt(3)
	v_mfma_f32_32x32x16_bf16 v[98:113], v[162:165], v[178:181], v[98:113]
	ds_read_b128 v[162:165], v216 offset:0x100
	v_mfma_f32_32x32x16_bf16 v[66:81], v[174:177], v[178:181], v[66:81]
	ds_read_b128 v[174:177], v216 offset:0x3100
	ds_read_b128 v[178:181], v199 offset:0x800
	s_waitcnt lgkmcnt(3)
	v_mfma_f32_32x32x16_bf16 v[98:113], v[166:169], v[232:235], v[98:113]
	ds_read_b128 v[166:169], v217 offset:0x100
	v_mfma_f32_32x32x16_bf16 v[66:81], v[170:173], v[232:235], v[66:81]
	ds_read_b128 v[170:173], v217 offset:0x3100
	ds_read_b128 v[232:235], v199 offset:0xc00
	s_waitcnt lgkmcnt(3)
	v_mfma_f32_32x32x16_bf16 v[98:113], v[162:165], v[178:181], v[98:113]
	s_waitcnt lgkmcnt(0)
	v_mfma_f32_32x32x16_bf16 v[66:81], v[174:177], v[178:181], v[66:81]
	v_mfma_f32_32x32x16_bf16 v[98:113], v[166:169], v[232:235], v[98:113]
	v_mfma_f32_32x32x16_bf16 v[66:81], v[170:173], v[232:235], v[66:81]
	s_nop 10
	v_max_f32_e32 v162, v98, v102
	v_max_f32_e32 v163, v99, v103
	v_max_f32_e32 v164, v101, v105
	v_max3_f32 v165, v100, v104, v108
	v_max3_f32 v164, v164, v109, v113
	v_max3_f32 v162, v162, v106, v110
	v_max3_f32 v163, v163, v107, v111
	v_max3_f32 v165, v165, v112, v68
	v_max3_f32 v164, v164, v69, v73
	v_max3_f32 v162, v162, v66, v70
	v_max3_f32 v163, v163, v67, v71
	v_max3_f32 v165, v165, v72, v76
	v_max3_f32 v164, v164, v77, v81
	v_max3_f32 v162, v162, v74, v78
	v_max3_f32 v163, v163, v75, v79
	v_max3_f32 v164, v165, v80, v164
	v_max3_f32 v162, v162, v163, v164
	v_cmp_ge_f32_e32 vcc, s48, v162
	s_cmp_eq_u64 vcc, exec
	v_mov_b32_e32 v223, 1.0
	s_cbranch_scc0 .LBB0_375
	v_mov_b32_e32 v226, v228

; template <bool FIRST>
; __device__ __forceinline__ void partialSM(f32x16& p0, f32x16& p1, float& mC, float& alpha) {
;     ...
;   { auto rr = __builtin_amdgcn_permlane32_swap(__float_as_uint(pmax), __float_as_uint(pmax), false, false);
;     pmax = fmaxf(__uint_as_float(rr[0]), __uint_as_float(rr[1])); }
;   if (!FIRST && __builtin_expect(__all(pmax <= THR2), 1)) { alpha = 1.f; }
;   else { const float delta = FIRST ? fmaxf(pmax, -200.f) : fmaxf(pmax, 0.f); alpha = FIRST ? 1.f : __builtin_amdgcn_exp2f(-delta); mC += delta;
; #pragma unroll
;     for (int r = 0; r < 16; ++r) p0[r] -= delta;
; #pragma unroll
;     for (int r = 0; r < 16; ++r) p1[r] -= delta; }
.LBB0_374:
	v_mov_b32_e32 v163, v162
	s_nop 1
	v_permlane32_swap_b32_e32 v162, v163
	v_max_f32_e32 v162, v162, v163
	v_max_f32_e32 v162, v162, v162
	v_max_f32_e32 v162, 0, v162
	v_exp_f32_e64 v227, -v162
	v_add_f32_e32 v228, v226, v162
	v_pk_add_f32 v[98:99], v[98:99], v[162:163] op_sel_hi:[1,0] neg_lo:[0,1] neg_hi:[0,1]
	v_pk_add_f32 v[100:101], v[100:101], v[162:163] op_sel_hi:[1,0] neg_lo:[0,1] neg_hi:[0,1]
	v_pk_add_f32 v[102:103], v[102:103], v[162:163] op_sel_hi:[1,0] neg_lo:[0,1] neg_hi:[0,1]
	v_pk_add_f32 v[104:105], v[104:105], v[162:163] op_sel_hi:[1,0] neg_lo:[0,1] neg_hi:[0,1]
	v_pk_add_f32 v[106:107], v[106:107], v[162:163] op_sel_hi:[1,0] neg_lo:[0,1] neg_hi:[0,1]
	v_pk_add_f32 v[108:109], v[108:109], v[162:163] op_sel_hi:[1,0] neg_lo:[0,1] neg_hi:[0,1]
	v_pk_add_f32 v[110:111], v[110:111], v[162:163] op_sel_hi:[1,0] neg_lo:[0,1] neg_hi:[0,1]
	v_pk_add_f32 v[112:113], v[112:113], v[162:163] op_sel_hi:[1,0] neg_lo:[0,1] neg_hi:[0,1]
	v_sub_f32_e32 v97, v97, v162
	v_sub_f32_e32 v96, v96, v162
	v_sub_f32_e32 v95, v95, v162
	v_sub_f32_e32 v94, v94, v162
	v_sub_f32_e32 v93, v93, v162
	v_sub_f32_e32 v92, v92, v162
	v_sub_f32_e32 v91, v91, v162
	v_sub_f32_e32 v90, v90, v162
	v_sub_f32_e32 v89, v89, v162
	v_sub_f32_e32 v88, v88, v162
	v_sub_f32_e32 v87, v87, v162
	v_sub_f32_e32 v86, v86, v162
	v_sub_f32_e32 v85, v85, v162
	v_sub_f32_e32 v84, v84, v162
	v_sub_f32_e32 v83, v83, v162
	v_sub_f32_e32 v82, v82, v162
	s_branch .LBB0_362
.LBB0_375:
	v_mov_b32_e32 v163, v162
	s_nop 1
	v_permlane32_swap_b32_e32 v162, v163
	v_max_f32_e32 v162, v162, v163
	v_max_f32_e32 v162, v162, v162
	v_max_f32_e32 v162, 0, v162
	v_exp_f32_e64 v223, -v162
	v_add_f32_e32 v226, v228, v162
	v_pk_add_f32 v[98:99], v[98:99], v[162:163] op_sel_hi:[1,0] neg_lo:[0,1] neg_hi:[0,1]
	v_pk_add_f32 v[100:101], v[100:101], v[162:163] op_sel_hi:[1,0] neg_lo:[0,1] neg_hi:[0,1]
	v_pk_add_f32 v[102:103], v[102:103], v[162:163] op_sel_hi:[1,0] neg_lo:[0,1] neg_hi:[0,1]
	v_pk_add_f32 v[104:105], v[104:105], v[162:163] op_sel_hi:[1,0] neg_lo:[0,1] neg_hi:[0,1]
	v_pk_add_f32 v[106:107], v[106:107], v[162:163] op_sel_hi:[1,0] neg_lo:[0,1] neg_hi:[0,1]
	v_pk_add_f32 v[108:109], v[108:109], v[162:163] op_sel_hi:[1,0] neg_lo:[0,1] neg_hi:[0,1]
	v_pk_add_f32 v[110:111], v[110:111], v[162:163] op_sel_hi:[1,0] neg_lo:[0,1] neg_hi:[0,1]
	v_pk_add_f32 v[112:113], v[112:113], v[162:163] op_sel_hi:[1,0] neg_lo:[0,1] neg_hi:[0,1]
	v_sub_f32_e32 v81, v81, v162
	v_sub_f32_e32 v80, v80, v162
	v_sub_f32_e32 v79, v79, v162
	v_sub_f32_e32 v78, v78, v162
	v_sub_f32_e32 v77, v77, v162
	v_sub_f32_e32 v76, v76, v162
	v_sub_f32_e32 v75, v75, v162
	v_sub_f32_e32 v74, v74, v162
	v_sub_f32_e32 v73, v73, v162
	v_sub_f32_e32 v72, v72, v162
	v_sub_f32_e32 v71, v71, v162
	v_sub_f32_e32 v70, v70, v162
	v_sub_f32_e32 v69, v69, v162
	v_sub_f32_e32 v68, v68, v162
	v_sub_f32_e32 v67, v67, v162
	v_sub_f32_e32 v66, v66, v162
	s_branch .LBB0_368

; __device__ __forceinline__ void qkt12_roll(f32x16& p0, f32x16& p1, const f32x16& negm, int kb, int qa, const bf16x8* qr) {
;   const int a0 = kb ^ (0 << 5); const bf16x8 x0 = lds_rd128<0>(a0), y0 = lds_rd128<12288>(a0);
;   const int a1 = kb ^ (1 << 5); const bf16x8 x1 = lds_rd128<0>(a1), y1 = lds_rd128<12288>(a1);
;   asm volatile("s_waitcnt lgkmcnt(2)" ::: "memory"); SBAR();
;   p0 = __builtin_amdgcn_mfma_f32_32x32x16_bf16(x0, qr[0], negm, 0, 0, 0); p1 = __builtin_amdgcn_mfma_f32_32x32x16_bf16(y0, qr[0], negm, 0, 0, 0);
;   const int a2 = kb ^ (2 << 5); const bf16x8 x2 = lds_rd128<0>(a2), y2 = lds_rd128<12288>(a2);
;   asm volatile("s_waitcnt lgkmcnt(2)" ::: "memory"); SBAR();
;   p0 = __builtin_amdgcn_mfma_f32_32x32x16_bf16(x1, qr[1], p0, 0, 0, 0); p1 = __builtin_amdgcn_mfma_f32_32x32x16_bf16(y1, qr[1], p1, 0, 0, 0);
;   const int a3 = kb ^ (3 << 5); const bf16x8 x3 = lds_rd128<0>(a3), y3 = lds_rd128<12288>(a3);
;   asm volatile("s_waitcnt lgkmcnt(2)" ::: "memory"); SBAR();
;   p0 = __builtin_amdgcn_mfma_f32_32x32x16_bf16(x2, qr[2], p0, 0, 0, 0); p1 = __builtin_amdgcn_mfma_f32_32x32x16_bf16(y2, qr[2], p1, 0, 0, 0);
;   const int a4 = kb ^ (0 << 5); const bf16x8 x4 = lds_rd128<128>(a4), y4 = lds_rd128<12416>(a4);
;   asm volatile("s_waitcnt lgkmcnt(2)" ::: "memory"); SBAR();
;   p0 = __builtin_amdgcn_mfma_f32_32x32x16_bf16(x3, qr[3], p0, 0, 0, 0); p1 = __builtin_amdgcn_mfma_f32_32x32x16_bf16(y3, qr[3], p1, 0, 0, 0);
;   const int a5 = kb ^ (1 << 5); const bf16x8 x5 = lds_rd128<128>(a5), y5 = lds_rd128<12416>(a5);
;   asm volatile("s_waitcnt lgkmcnt(2)" ::: "memory"); SBAR();
;   p0 = __builtin_amdgcn_mfma_f32_32x32x16_bf16(x4, qr[4], p0, 0, 0, 0); p1 = __builtin_amdgcn_mfma_f32_32x32x16_bf16(y4, qr[4], p1, 0, 0, 0);
;   const int a6 = kb ^ (2 << 5); const bf16x8 x6 = lds_rd128<128>(a6), y6 = lds_rd128<12416>(a6);
;   asm volatile("s_waitcnt lgkmcnt(2)" ::: "memory"); SBAR();
;   p0 = __builtin_amdgcn_mfma_f32_32x32x16_bf16(x5, qr[5], p0, 0, 0, 0); p1 = __builtin_amdgcn_mfma_f32_32x32x16_bf16(y5, qr[5], p1, 0, 0, 0);
;   const int a7 = kb ^ (3 << 5); const bf16x8 x7 = lds_rd128<128>(a7), y7 = lds_rd128<12416>(a7);
;   asm volatile("s_waitcnt lgkmcnt(2)" ::: "memory"); SBAR();
;   p0 = __builtin_amdgcn_mfma_f32_32x32x16_bf16(x6, qr[6], p0, 0, 0, 0); p1 = __builtin_amdgcn_mfma_f32_32x32x16_bf16(y6, qr[6], p1, 0, 0, 0);
.LBB0_386:
	v_cmp_neq_f32_e64 s[6:7], v228, -v225
	s_cmp_eq_u64 s[6:7], 0
	s_cselect_b64 s[6:7], -1, 0
	v_cndmask_b32_e64 v113, -v225, v113, s[6:7]
	v_cndmask_b32_e64 v112, -v225, v112, s[6:7]
	v_cndmask_b32_e64 v111, -v225, v111, s[6:7]
	v_cndmask_b32_e64 v110, -v225, v110, s[6:7]
	v_cndmask_b32_e64 v109, -v225, v109, s[6:7]
	v_cndmask_b32_e64 v108, -v225, v108, s[6:7]
	v_cndmask_b32_e64 v107, -v225, v107, s[6:7]
	v_cndmask_b32_e64 v106, -v225, v106, s[6:7]
	v_cndmask_b32_e64 v105, -v225, v105, s[6:7]
	v_cndmask_b32_e64 v104, -v225, v104, s[6:7]
	v_cndmask_b32_e64 v103, -v225, v103, s[6:7]
	v_cndmask_b32_e64 v102, -v225, v102, s[6:7]
	v_cndmask_b32_e64 v101, -v225, v101, s[6:7]
	v_cndmask_b32_e64 v100, -v225, v100, s[6:7]
	v_cndmask_b32_e64 v99, -v225, v99, s[6:7]
	v_cndmask_b32_e64 v98, -v225, v98, s[6:7]
	ds_read_b128 v[82:85], v221 offset:0
	ds_read_b128 v[230:233], v221 offset:0x3000
	ds_read_b128 v[234:237], v220 offset:0
	ds_read_b128 v[238:241], v220 offset:0x3000
	s_waitcnt lgkmcnt(2)
	s_nop 1
	v_mfma_f32_32x32x16_bf16 v[114:129], v[82:85], v[158:161], v[98:113]
	v_mfma_f32_32x32x16_bf16 v[82:97], v[230:233], v[158:161], v[98:113]
	ds_read_b128 v[230:233], v219 offset:0
	ds_read_b128 v[242:245], v219 offset:0x3000
	s_waitcnt lgkmcnt(2)
	v_mfma_f32_32x32x16_bf16 v[114:129], v[234:237], v[154:157], v[114:129]
	ds_read_b128 v[234:237], v218 offset:0
	v_mfma_f32_32x32x16_bf16 v[82:97], v[238:241], v[154:157], v[82:97]
	ds_read_b128 v[238:241], v218 offset:0x3000
	s_waitcnt lgkmcnt(2)
	v_mfma_f32_32x32x16_bf16 v[114:129], v[230:233], v[150:153], v[114:129]
	ds_read_b128 v[230:233], v221 offset:0x80
	v_mfma_f32_32x32x16_bf16 v[82:97], v[242:245], v[150:153], v[82:97]
	ds_read_b128 v[242:245], v221 offset:0x3080
	s_waitcnt lgkmcnt(2)
	v_mfma_f32_32x32x16_bf16 v[114:129], v[234:237], v[146:149], v[114:129]
	ds_read_b128 v[234:237], v220 offset:0x80
	v_mfma_f32_32x32x16_bf16 v[82:97], v[238:241], v[146:149], v[82:97]
	ds_read_b128 v[238:241], v220 offset:0x3080
	s_waitcnt lgkmcnt(2)
	v_mfma_f32_32x32x16_bf16 v[114:129], v[230:233], v[142:145], v[114:129]
	ds_read_b128 v[230:233], v219 offset:0x80
	v_mfma_f32_32x32x16_bf16 v[82:97], v[242:245], v[142:145], v[82:97]
	ds_read_b128 v[242:245], v219 offset:0x3080
	s_waitcnt lgkmcnt(2)
	v_mfma_f32_32x32x16_bf16 v[114:129], v[234:237], v[138:141], v[114:129]
	ds_read_b128 v[234:237], v218 offset:0x80
	v_mfma_f32_32x32x16_bf16 v[82:97], v[238:241], v[138:141], v[82:97]
	ds_read_b128 v[238:241], v218 offset:0x3080
	s_waitcnt lgkmcnt(2)
	v_mfma_f32_32x32x16_bf16 v[114:129], v[230:233], v[134:137], v[114:129]
	ds_read_b128 v[230:233], v221 offset:0x100
	v_mfma_f32_32x32x16_bf16 v[82:97], v[242:245], v[134:137], v[82:97]
	ds_read_b128 v[242:245], v221 offset:0x3100
	ds_read_b128 v[246:249], v199 offset:0
	s_waitcnt lgkmcnt(3)
	v_mfma_f32_32x32x16_bf16 v[114:129], v[234:237], v[130:133], v[114:129]
	ds_read_b128 v[234:237], v220 offset:0x100
	v_mfma_f32_32x32x16_bf16 v[82:97], v[238:241], v[130:133], v[82:97]
	ds_read_b128 v[238:241], v220 offset:0x3100
	ds_read_b128 v[250:253], v199 offset:0x400
	s_waitcnt lgkmcnt(3)
	v_mfma_f32_32x32x16_bf16 v[114:129], v[230:233], v[246:249], v[114:129]
	ds_read_b128 v[230:233], v219 offset:0x100
	v_mfma_f32_32x32x16_bf16 v[82:97], v[242:245], v[246:249], v[82:97]
	ds_read_b128 v[242:245], v219 offset:0x3100
	ds_read_b128 v[246:249], v199 offset:0x800
	s_waitcnt lgkmcnt(3)
	v_mfma_f32_32x32x16_bf16 v[114:129], v[234:237], v[250:253], v[114:129]
	ds_read_b128 v[234:237], v218 offset:0x100
	v_mfma_f32_32x32x16_bf16 v[82:97], v[238:241], v[250:253], v[82:97]
	ds_read_b128 v[238:241], v218 offset:0x3100
	ds_read_b128 v[250:253], v199 offset:0xc00
	s_waitcnt lgkmcnt(3)
	v_mfma_f32_32x32x16_bf16 v[114:129], v[230:233], v[246:249], v[114:129]
	s_waitcnt lgkmcnt(0)
; __device__ __forceinline__ void pv_d0(f32x16* o, int vb, bf16x8 pa0, bf16x8 pa1, bf16x8 pa2, bf16x8 pa3) {
;     ...
;   const s16x4 l0 = tr_read<v_rd_off(0, 0, 0)>(vb), h0 = tr_read<v_rd_off(0, 0, 1)>(vb);
;   const s16x4 l1 = tr_read<v_rd_off(0, 1, 0)>(vb), h1 = tr_read<v_rd_off(0, 1, 1)>(vb);
;   const s16x4 l2 = tr_read<v_rd_off(0, 2, 0)>(vb), h2 = tr_read<v_rd_off(0, 2, 1)>(vb);
;   const s16x4 l3 = tr_read<v_rd_off(0, 3, 0)>(vb), h3 = tr_read<v_rd_off(0, 3, 1)>(vb);
;   const s16x4 l4 = tr_read<v_rd_off(1, 0, 0)>(vb), h4 = tr_read<v_rd_off(1, 0, 1)>(vb);
;   asm volatile("s_waitcnt lgkmcnt(8)" ::: "memory"); SBAR();
;   o[0] = __builtin_amdgcn_mfma_f32_32x32x16_bf16(pa0, PK(l0, h0), o[0], 0, 0, 0);
;   const s16x4 l5 = tr_read<v_rd_off(1, 1, 0)>(vb), h5 = tr_read<v_rd_off(1, 1, 1)>(vb);
;   asm volatile("s_waitcnt lgkmcnt(8)" ::: "memory"); SBAR();
;   o[0] = __builtin_amdgcn_mfma_f32_32x32x16_bf16(pa1, PK(l1, h1), o[0], 0, 0, 0);
;   const s16x4 l6 = tr_read<v_rd_off(1, 2, 0)>(vb), h6 = tr_read<v_rd_off(1, 2, 1)>(vb);
;   asm volatile("s_waitcnt lgkmcnt(8)" ::: "memory"); SBAR();
;   o[0] = __builtin_amdgcn_mfma_f32_32x32x16_bf16(pa2, PK(l2, h2), o[0], 0, 0, 0);
;   const s16x4 l7 = tr_read<v_rd_off(1, 3, 0)>(vb), h7 = tr_read<v_rd_off(1, 3, 1)>(vb);
;   asm volatile("s_waitcnt lgkmcnt(8)" ::: "memory"); SBAR();
;   o[0] = __builtin_amdgcn_mfma_f32_32x32x16_bf16(pa3, PK(l3, h3), o[0], 0, 0, 0);
;   const s16x4 l8 = tr_read<v_rd_off(2, 0, 0)>(vb), h8 = tr_read<v_rd_off(2, 0, 1)>(vb);
;   asm volatile("s_waitcnt lgkmcnt(8)" ::: "memory"); SBAR();
;   o[1] = __builtin_amdgcn_mfma_f32_32x32x16_bf16(pa0, PK(l4, h4), o[1], 0, 0, 0);
;   const s16x4 l9 = tr_read<v_rd_off(2, 1, 0)>(vb), h9 = tr_read<v_rd_off(2, 1, 1)>(vb);
;   asm volatile("s_waitcnt lgkmcnt(8)" ::: "memory"); SBAR();
;   o[1] = __builtin_amdgcn_mfma_f32_32x32x16_bf16(pa1, PK(l5, h5), o[1], 0, 0, 0);
;   const s16x4 l10 = tr_read<v_rd_off(2, 2, 0)>(vb), h10 = tr_read<v_rd_off(2, 2, 1)>(vb);
;   asm volatile("s_waitcnt lgkmcnt(8)" ::: "memory"); SBAR();
;   o[1] = __builtin_amdgcn_mfma_f32_32x32x16_bf16(pa2, PK(l6, h6), o[1], 0, 0, 0);
;   const s16x4 l11 = tr_read<v_rd_off(2, 3, 0)>(vb), h11 = tr_read<v_rd_off(2, 3, 1)>(vb);
;   asm volatile("s_waitcnt lgkmcnt(8)" ::: "memory"); SBAR();
;   o[1] = __builtin_amdgcn_mfma_f32_32x32x16_bf16(pa3, PK(l7, h7), o[1], 0, 0, 0);
	v_mfma_f32_32x32x16_bf16 v[82:97], v[242:245], v[246:249], v[82:97]
	v_mfma_f32_32x32x16_bf16 v[114:129], v[234:237], v[250:253], v[114:129]
	v_mfma_f32_32x32x16_bf16 v[82:97], v[238:241], v[250:253], v[82:97]
	v_exp_f32_e32 v66, v66
	v_exp_f32_e32 v67, v67
	v_exp_f32_e32 v68, v68
	v_exp_f32_e32 v69, v69
	v_exp_f32_e32 v70, v70
	v_exp_f32_e32 v71, v71
	v_exp_f32_e32 v72, v72
	v_exp_f32_e32 v73, v73
	v_add_f32_e32 v166, v168, v176
	v_add_f32_e32 v179, v175, v178
	v_add_f32_e32 v180, v169, v167
	v_add_f32_e32 v181, v174, v177
	v_exp_f32_e32 v74, v74
	v_exp_f32_e32 v75, v75
	v_exp_f32_e32 v76, v76
	v_exp_f32_e32 v77, v77
	v_add_f32_e32 v166, v170, v166
	v_add_f32_e32 v179, v173, v179
	v_add_f32_e32 v180, v165, v180
	v_add_f32_e32 v181, v171, v181
	v_exp_f32_e32 v78, v78
	v_exp_f32_e32 v79, v79
	v_exp_f32_e32 v80, v80
	v_exp_f32_e32 v81, v81
	v_add_f32_e32 v166, v163, v166
	v_add_f32_e32 v179, v172, v179
	v_add_f32_e32 v180, v162, v180
	v_add_f32_e32 v181, v164, v181
	v_add_f32_e32 v166, v66, v166
	v_add_f32_e32 v179, v67, v179
	v_add_f32_e32 v180, v68, v180
	v_add_f32_e32 v181, v69, v181
	v_add_f32_e32 v166, v70, v166
	v_add_f32_e32 v179, v71, v179
	v_add_f32_e32 v180, v72, v180
	v_add_f32_e32 v181, v73, v181
	v_add_f32_e32 v166, v74, v166
	v_add_f32_e32 v179, v75, v179
	v_add_f32_e32 v180, v76, v180
	v_add_f32_e32 v181, v77, v181
	v_add_f32_e32 v166, v78, v166
	v_add_f32_e32 v179, v79, v179
	v_add_f32_e32 v180, v80, v180
	v_add_f32_e32 v181, v81, v181
	v_add_f32_e32 v166, v166, v179
	v_add_f32_e32 v179, v180, v181
	v_add_f32_e32 v223, v166, v179
	v_mov_b32_e32 v224, v223
	v_cvt_pk_bf16_f32 v166, v176, v178
	v_cvt_pk_bf16_f32 v167, v167, v177
	v_cvt_pk_bf16_f32 v168, v168, v175
	s_nop 1
	v_permlane32_swap_b32_e32 v223, v224
	v_cvt_pk_bf16_f32 v169, v169, v174
	v_cvt_pk_bf16_f32 v170, v170, v173
	v_cvt_pk_bf16_f32 v171, v165, v171
	v_cvt_pk_bf16_f32 v172, v163, v172
	v_cvt_pk_bf16_f32 v173, v162, v164
	v_cvt_pk_bf16_f32 v174, v66, v67
	v_cvt_pk_bf16_f32 v175, v68, v69
	v_cvt_pk_bf16_f32 v176, v70, v71
	v_cvt_pk_bf16_f32 v177, v72, v73
	v_cvt_pk_bf16_f32 v178, v74, v75
	v_cvt_pk_bf16_f32 v179, v76, v77
	v_cvt_pk_bf16_f32 v180, v78, v79
	v_cvt_pk_bf16_f32 v181, v80, v81
	v_lshl_add_u64 v[190:191], s[42:43], 0, v[188:189]
	v_add_co_u32_e32 v70, vcc, s49, v190
	v_lshl_add_u64 v[196:197], s[42:43], 0, v[186:187]
	s_nop 0
	v_addc_co_u32_e32 v71, vcc, 0, v191, vcc
	v_add_co_u32_e32 v74, vcc, s28, v190
	s_nop 1
	v_addc_co_u32_e32 v75, vcc, 0, v191, vcc
	global_load_dwordx4 v[66:69], v[70:71], off offset:256
	s_nop 0
	global_load_dwordx4 v[70:73], v[70:71], off
	s_nop 0
	global_load_dwordx4 v[78:81], v[74:75], off offset:256
	s_nop 0
	global_load_dwordx4 v[74:77], v[74:75], off
	v_add_co_u32_e32 v162, vcc, s68, v196
	s_nop 1
	v_addc_co_u32_e32 v163, vcc, 0, v197, vcc
	global_load_dwordx4 v[162:165], v[162:163], off
	ds_read_b64_tr_b16 v[230:231], v201 offset:0
	ds_read_b64_tr_b16 v[232:233], v201 offset:0x800
	ds_read_b64_tr_b16 v[234:235], v201 offset:0x1000
	ds_read_b64_tr_b16 v[236:237], v201 offset:0x1800
	ds_read_b64_tr_b16 v[238:239], v201 offset:0x2000
	ds_read_b64_tr_b16 v[240:241], v201 offset:0x2800
	ds_read_b64_tr_b16 v[242:243], v201 offset:0x3000
	ds_read_b64_tr_b16 v[244:245], v201 offset:0x3800
	ds_read_b64_tr_b16 v[246:247], v201 offset:0x200
	ds_read_b64_tr_b16 v[248:249], v201 offset:0xa00
	s_waitcnt lgkmcnt(8)
	s_nop 0
	v_mfma_f32_32x32x16_bf16 v[2:17], v[166:169], v[230:233], v[2:17]
	ds_read_b64_tr_b16 v[230:231], v201 offset:0x1200
	ds_read_b64_tr_b16 v[232:233], v201 offset:0x1a00
	s_waitcnt lgkmcnt(8)
	v_mfma_f32_32x32x16_bf16 v[2:17], v[170:173], v[234:237], v[2:17]
	ds_read_b64_tr_b16 v[234:235], v201 offset:0x2200
	ds_read_b64_tr_b16 v[236:237], v201 offset:0x2a00
	s_waitcnt lgkmcnt(8)
	v_mfma_f32_32x32x16_bf16 v[2:17], v[174:177], v[238:241], v[2:17]
	ds_read_b64_tr_b16 v[238:239], v201 offset:0x3200
	ds_read_b64_tr_b16 v[240:241], v201 offset:0x3a00
	s_waitcnt lgkmcnt(8)
	v_mfma_f32_32x32x16_bf16 v[2:17], v[178:181], v[242:245], v[2:17]
	ds_read_b64_tr_b16 v[242:243], v201 offset:0x400
	ds_read_b64_tr_b16 v[244:245], v201 offset:0xc00
	s_waitcnt lgkmcnt(8)
	v_mfma_f32_32x32x16_bf16 v[50:65], v[166:169], v[246:249], v[50:65]
	ds_read_b64_tr_b16 v[246:247], v201 offset:0x1400
	ds_read_b64_tr_b16 v[248:249], v201 offset:0x1c00
	s_waitcnt lgkmcnt(8)
	v_mfma_f32_32x32x16_bf16 v[50:65], v[170:173], v[230:233], v[50:65]
	ds_read_b64_tr_b16 v[230:231], v201 offset:0x2400
	ds_read_b64_tr_b16 v[232:233], v201 offset:0x2c00
	s_waitcnt lgkmcnt(8)
	v_mfma_f32_32x32x16_bf16 v[50:65], v[174:177], v[234:237], v[50:65]
	ds_read_b64_tr_b16 v[234:235], v201 offset:0x3400
	ds_read_b64_tr_b16 v[236:237], v201 offset:0x3c00
	s_waitcnt lgkmcnt(8)
	v_mfma_f32_32x32x16_bf16 v[50:65], v[178:181], v[238:241], v[50:65]
	ds_read_b64_tr_b16 v[238:239], v201 offset:0x600
	ds_read_b64_tr_b16 v[240:241], v201 offset:0xe00
	s_waitcnt lgkmcnt(8)
	v_mfma_f32_32x32x16_bf16 v[34:49], v[166:169], v[242:245], v[34:49]
	ds_read_b64_tr_b16 v[242:243], v201 offset:0x1600
	ds_read_b64_tr_b16 v[244:245], v201 offset:0x1e00
	s_waitcnt lgkmcnt(8)
	v_mfma_f32_32x32x16_bf16 v[34:49], v[170:173], v[246:249], v[34:49]
	ds_read_b64_tr_b16 v[246:247], v201 offset:0x2600
	ds_read_b64_tr_b16 v[248:249], v201 offset:0x2e00
	s_waitcnt lgkmcnt(8)
	v_mfma_f32_32x32x16_bf16 v[34:49], v[174:177], v[230:233], v[34:49]
	ds_read_b64_tr_b16 v[230:231], v201 offset:0x3600
	ds_read_b64_tr_b16 v[232:233], v201 offset:0x3e00
	s_waitcnt lgkmcnt(8)
	v_mfma_f32_32x32x16_bf16 v[34:49], v[178:181], v[234:237], v[34:49]
	s_waitcnt lgkmcnt(6)
	v_mfma_f32_32x32x16_bf16 v[18:33], v[166:169], v[238:241], v[18:33]
	s_waitcnt lgkmcnt(4)
	v_mfma_f32_32x32x16_bf16 v[18:33], v[170:173], v[242:245], v[18:33]
	s_waitcnt lgkmcnt(2)
	v_mfma_f32_32x32x16_bf16 v[18:33], v[174:177], v[246:249], v[18:33]
	s_waitcnt lgkmcnt(0)
	v_max_f32_e32 v166, v114, v118
	v_max_f32_e32 v167, v115, v119
	v_max_f32_e32 v168, v117, v121
	v_max3_f32 v169, v116, v120, v124
	v_max3_f32 v168, v168, v125, v129
	v_max3_f32 v166, v166, v122, v126
	v_max3_f32 v167, v167, v123, v127
	v_max3_f32 v169, v169, v128, v84
	v_max3_f32 v168, v168, v85, v89
	v_max3_f32 v166, v166, v82, v86
	v_max3_f32 v167, v167, v83, v87
	v_max3_f32 v169, v169, v88, v92
	v_max3_f32 v168, v168, v93, v97
	v_mfma_f32_32x32x16_bf16 v[18:33], v[178:181], v[230:233], v[18:33]
	v_max3_f32 v166, v166, v90, v94
	v_max3_f32 v167, v167, v91, v95
	v_max3_f32 v168, v169, v96, v168
	v_max3_f32 v166, v166, v167, v168
	v_cmp_ge_f32_e32 vcc, s48, v166
	s_cmp_eq_u64 vcc, exec
	s_cbranch_scc0 .LBB0_400
	v_mov_b32_e32 v227, v225
	v_mov_b32_e32 v226, 1.0

; __device__ __forceinline__ void qkt12_roll(f32x16& p0, f32x16& p1, const f32x16& negm, int kb, int qa, const bf16x8* qr) {
;   const int a0 = kb ^ (0 << 5); const bf16x8 x0 = lds_rd128<0>(a0), y0 = lds_rd128<12288>(a0);
;   const int a1 = kb ^ (1 << 5); const bf16x8 x1 = lds_rd128<0>(a1), y1 = lds_rd128<12288>(a1);
;   asm volatile("s_waitcnt lgkmcnt(2)" ::: "memory"); SBAR();
;   p0 = __builtin_amdgcn_mfma_f32_32x32x16_bf16(x0, qr[0], negm, 0, 0, 0); p1 = __builtin_amdgcn_mfma_f32_32x32x16_bf16(y0, qr[0], negm, 0, 0, 0);
;   const int a2 = kb ^ (2 << 5); const bf16x8 x2 = lds_rd128<0>(a2), y2 = lds_rd128<12288>(a2);
;   asm volatile("s_waitcnt lgkmcnt(2)" ::: "memory"); SBAR();
;   p0 = __builtin_amdgcn_mfma_f32_32x32x16_bf16(x1, qr[1], p0, 0, 0, 0); p1 = __builtin_amdgcn_mfma_f32_32x32x16_bf16(y1, qr[1], p1, 0, 0, 0);
;   const int a3 = kb ^ (3 << 5); const bf16x8 x3 = lds_rd128<0>(a3), y3 = lds_rd128<12288>(a3);
;   asm volatile("s_waitcnt lgkmcnt(2)" ::: "memory"); SBAR();
;   p0 = __builtin_amdgcn_mfma_f32_32x32x16_bf16(x2, qr[2], p0, 0, 0, 0); p1 = __builtin_amdgcn_mfma_f32_32x32x16_bf16(y2, qr[2], p1, 0, 0, 0);
;   const int a4 = kb ^ (0 << 5); const bf16x8 x4 = lds_rd128<128>(a4), y4 = lds_rd128<12416>(a4);
;   asm volatile("s_waitcnt lgkmcnt(2)" ::: "memory"); SBAR();
;   p0 = __builtin_amdgcn_mfma_f32_32x32x16_bf16(x3, qr[3], p0, 0, 0, 0); p1 = __builtin_amdgcn_mfma_f32_32x32x16_bf16(y3, qr[3], p1, 0, 0, 0);
;   const int a5 = kb ^ (1 << 5); const bf16x8 x5 = lds_rd128<128>(a5), y5 = lds_rd128<12416>(a5);
;   asm volatile("s_waitcnt lgkmcnt(2)" ::: "memory"); SBAR();
;   p0 = __builtin_amdgcn_mfma_f32_32x32x16_bf16(x4, qr[4], p0, 0, 0, 0); p1 = __builtin_amdgcn_mfma_f32_32x32x16_bf16(y4, qr[4], p1, 0, 0, 0);
;   const int a6 = kb ^ (2 << 5); const bf16x8 x6 = lds_rd128<128>(a6), y6 = lds_rd128<12416>(a6);
;   asm volatile("s_waitcnt lgkmcnt(2)" ::: "memory"); SBAR();
;   p0 = __builtin_amdgcn_mfma_f32_32x32x16_bf16(x5, qr[5], p0, 0, 0, 0); p1 = __builtin_amdgcn_mfma_f32_32x32x16_bf16(y5, qr[5], p1, 0, 0, 0);
;   const int a7 = kb ^ (3 << 5); const bf16x8 x7 = lds_rd128<128>(a7), y7 = lds_rd128<12416>(a7);
;   asm volatile("s_waitcnt lgkmcnt(2)" ::: "memory"); SBAR();
;   p0 = __builtin_amdgcn_mfma_f32_32x32x16_bf16(x6, qr[6], p0, 0, 0, 0); p1 = __builtin_amdgcn_mfma_f32_32x32x16_bf16(y6, qr[6], p1, 0, 0, 0);
.LBB0_392:
	v_xor_b32_e32 v66, 0x80000000, v225
	v_cndmask_b32_e64 v228, v66, v228, s[6:7]
	v_exp_f32_e32 v166, v114
	v_exp_f32_e32 v167, v116
	v_exp_f32_e32 v165, v124
	v_exp_f32_e32 v163, v126
	v_exp_f32_e32 v162, v128
	v_exp_f32_e32 v164, v129
	v_cmp_neq_f32_e64 s[6:7], v228, -v227
	s_cmp_eq_u64 s[6:7], 0
	s_cselect_b64 s[6:7], -1, 0
	v_cndmask_b32_e64 v113, -v227, v113, s[6:7]
	v_cndmask_b32_e64 v112, -v227, v112, s[6:7]
	v_cndmask_b32_e64 v111, -v227, v111, s[6:7]
	v_cndmask_b32_e64 v110, -v227, v110, s[6:7]
	v_cndmask_b32_e64 v109, -v227, v109, s[6:7]
	v_cndmask_b32_e64 v108, -v227, v108, s[6:7]
	v_cndmask_b32_e64 v107, -v227, v107, s[6:7]
	v_cndmask_b32_e64 v106, -v227, v106, s[6:7]
	v_cndmask_b32_e64 v105, -v227, v105, s[6:7]
	v_cndmask_b32_e64 v104, -v227, v104, s[6:7]
	v_cndmask_b32_e64 v103, -v227, v103, s[6:7]
	v_cndmask_b32_e64 v102, -v227, v102, s[6:7]
	v_cndmask_b32_e64 v101, -v227, v101, s[6:7]
	v_cndmask_b32_e64 v100, -v227, v100, s[6:7]
	v_cndmask_b32_e64 v99, -v227, v99, s[6:7]
	v_cndmask_b32_e64 v98, -v227, v98, s[6:7]
	v_exp_f32_e32 v177, v115
	v_exp_f32_e32 v176, v117
	v_exp_f32_e32 v168, v118
	v_exp_f32_e32 v175, v119
	v_exp_f32_e32 v169, v120
	v_exp_f32_e32 v174, v121
	v_exp_f32_e32 v170, v122
	v_exp_f32_e32 v173, v123
	v_exp_f32_e32 v171, v125
	v_exp_f32_e32 v172, v127
	s_waitcnt lgkmcnt(0)
	s_barrier
	ds_read_b128 v[66:69], v209 offset:0
	ds_read_b128 v[178:181], v209 offset:0x3000
	ds_read_b128 v[230:233], v215 offset:0
	ds_read_b128 v[234:237], v215 offset:0x3000
	s_waitcnt lgkmcnt(2)
	s_nop 0
	v_mfma_f32_32x32x16_bf16 v[114:129], v[66:69], v[158:161], v[98:113]
	v_mfma_f32_32x32x16_bf16 v[66:81], v[178:181], v[158:161], v[98:113]
	ds_read_b128 v[178:181], v216 offset:0
	ds_read_b128 v[238:241], v216 offset:0x3000
	s_waitcnt lgkmcnt(2)
	v_mfma_f32_32x32x16_bf16 v[114:129], v[230:233], v[154:157], v[114:129]
	ds_read_b128 v[230:233], v217 offset:0
	v_mfma_f32_32x32x16_bf16 v[66:81], v[234:237], v[154:157], v[66:81]
	ds_read_b128 v[234:237], v217 offset:0x3000
	s_waitcnt lgkmcnt(2)
	v_mfma_f32_32x32x16_bf16 v[114:129], v[178:181], v[150:153], v[114:129]
	ds_read_b128 v[178:181], v209 offset:0x80
	v_mfma_f32_32x32x16_bf16 v[66:81], v[238:241], v[150:153], v[66:81]
	ds_read_b128 v[238:241], v209 offset:0x3080
	s_waitcnt lgkmcnt(2)
	v_mfma_f32_32x32x16_bf16 v[114:129], v[230:233], v[146:149], v[114:129]
	ds_read_b128 v[230:233], v215 offset:0x80
	v_mfma_f32_32x32x16_bf16 v[66:81], v[234:237], v[146:149], v[66:81]
	ds_read_b128 v[234:237], v215 offset:0x3080
	s_waitcnt lgkmcnt(2)
	v_mfma_f32_32x32x16_bf16 v[114:129], v[178:181], v[142:145], v[114:129]
	ds_read_b128 v[178:181], v216 offset:0x80
	v_mfma_f32_32x32x16_bf16 v[66:81], v[238:241], v[142:145], v[66:81]
	ds_read_b128 v[238:241], v216 offset:0x3080
	s_waitcnt lgkmcnt(2)
	v_mfma_f32_32x32x16_bf16 v[114:129], v[230:233], v[138:141], v[114:129]
	ds_read_b128 v[230:233], v217 offset:0x80
	v_mfma_f32_32x32x16_bf16 v[66:81], v[234:237], v[138:141], v[66:81]
	ds_read_b128 v[234:237], v217 offset:0x3080
	s_waitcnt lgkmcnt(2)
	v_mfma_f32_32x32x16_bf16 v[114:129], v[178:181], v[134:137], v[114:129]
	ds_read_b128 v[178:181], v209 offset:0x100
	v_mfma_f32_32x32x16_bf16 v[66:81], v[238:241], v[134:137], v[66:81]
	ds_read_b128 v[238:241], v209 offset:0x3100
	ds_read_b128 v[242:245], v199 offset:0
	s_waitcnt lgkmcnt(3)
	v_mfma_f32_32x32x16_bf16 v[114:129], v[230:233], v[130:133], v[114:129]
	ds_read_b128 v[230:233], v215 offset:0x100
	v_mfma_f32_32x32x16_bf16 v[66:81], v[234:237], v[130:133], v[66:81]
	ds_read_b128 v[234:237], v215 offset:0x3100
	ds_read_b128 v[246:249], v199 offset:0x400
	s_waitcnt lgkmcnt(3)
	v_mfma_f32_32x32x16_bf16 v[114:129], v[178:181], v[242:245], v[114:129]
	ds_read_b128 v[178:181], v216 offset:0x100
	v_mfma_f32_32x32x16_bf16 v[66:81], v[238:241], v[242:245], v[66:81]
	ds_read_b128 v[238:241], v216 offset:0x3100
	ds_read_b128 v[242:245], v199 offset:0x800
	s_waitcnt lgkmcnt(3)
	v_mfma_f32_32x32x16_bf16 v[114:129], v[230:233], v[246:249], v[114:129]
	ds_read_b128 v[230:233], v217 offset:0x100
	v_mfma_f32_32x32x16_bf16 v[66:81], v[234:237], v[246:249], v[66:81]
	ds_read_b128 v[234:237], v217 offset:0x3100
	ds_read_b128 v[246:249], v199 offset:0xc00
	s_waitcnt lgkmcnt(3)
	v_mfma_f32_32x32x16_bf16 v[114:129], v[178:181], v[242:245], v[114:129]
	s_waitcnt lgkmcnt(0)
; __device__ __forceinline__ void pv_d0(f32x16* o, int vb, bf16x8 pa0, bf16x8 pa1, bf16x8 pa2, bf16x8 pa3) {
;     ...
;   const s16x4 l0 = tr_read<v_rd_off(0, 0, 0)>(vb), h0 = tr_read<v_rd_off(0, 0, 1)>(vb);
;   const s16x4 l1 = tr_read<v_rd_off(0, 1, 0)>(vb), h1 = tr_read<v_rd_off(0, 1, 1)>(vb);
;   const s16x4 l2 = tr_read<v_rd_off(0, 2, 0)>(vb), h2 = tr_read<v_rd_off(0, 2, 1)>(vb);
;   const s16x4 l3 = tr_read<v_rd_off(0, 3, 0)>(vb), h3 = tr_read<v_rd_off(0, 3, 1)>(vb);
;   const s16x4 l4 = tr_read<v_rd_off(1, 0, 0)>(vb), h4 = tr_read<v_rd_off(1, 0, 1)>(vb);
;   asm volatile("s_waitcnt lgkmcnt(8)" ::: "memory"); SBAR();
;   o[0] = __builtin_amdgcn_mfma_f32_32x32x16_bf16(pa0, PK(l0, h0), o[0], 0, 0, 0);
;   const s16x4 l5 = tr_read<v_rd_off(1, 1, 0)>(vb), h5 = tr_read<v_rd_off(1, 1, 1)>(vb);
;   asm volatile("s_waitcnt lgkmcnt(8)" ::: "memory"); SBAR();
;   o[0] = __builtin_amdgcn_mfma_f32_32x32x16_bf16(pa1, PK(l1, h1), o[0], 0, 0, 0);
;   const s16x4 l6 = tr_read<v_rd_off(1, 2, 0)>(vb), h6 = tr_read<v_rd_off(1, 2, 1)>(vb);
;   asm volatile("s_waitcnt lgkmcnt(8)" ::: "memory"); SBAR();
;   o[0] = __builtin_amdgcn_mfma_f32_32x32x16_bf16(pa2, PK(l2, h2), o[0], 0, 0, 0);
;   const s16x4 l7 = tr_read<v_rd_off(1, 3, 0)>(vb), h7 = tr_read<v_rd_off(1, 3, 1)>(vb);
;   asm volatile("s_waitcnt lgkmcnt(8)" ::: "memory"); SBAR();
;   o[0] = __builtin_amdgcn_mfma_f32_32x32x16_bf16(pa3, PK(l3, h3), o[0], 0, 0, 0);
;   const s16x4 l8 = tr_read<v_rd_off(2, 0, 0)>(vb), h8 = tr_read<v_rd_off(2, 0, 1)>(vb);
;   asm volatile("s_waitcnt lgkmcnt(8)" ::: "memory"); SBAR();
;   o[1] = __builtin_amdgcn_mfma_f32_32x32x16_bf16(pa0, PK(l4, h4), o[1], 0, 0, 0);
;   const s16x4 l9 = tr_read<v_rd_off(2, 1, 0)>(vb), h9 = tr_read<v_rd_off(2, 1, 1)>(vb);
;   asm volatile("s_waitcnt lgkmcnt(8)" ::: "memory"); SBAR();
;   o[1] = __builtin_amdgcn_mfma_f32_32x32x16_bf16(pa1, PK(l5, h5), o[1], 0, 0, 0);
;   const s16x4 l10 = tr_read<v_rd_off(2, 2, 0)>(vb), h10 = tr_read<v_rd_off(2, 2, 1)>(vb);
;   asm volatile("s_waitcnt lgkmcnt(8)" ::: "memory"); SBAR();
;   o[1] = __builtin_amdgcn_mfma_f32_32x32x16_bf16(pa2, PK(l6, h6), o[1], 0, 0, 0);
;   const s16x4 l11 = tr_read<v_rd_off(2, 3, 0)>(vb), h11 = tr_read<v_rd_off(2, 3, 1)>(vb);
;   asm volatile("s_waitcnt lgkmcnt(8)" ::: "memory"); SBAR();
;   o[1] = __builtin_amdgcn_mfma_f32_32x32x16_bf16(pa3, PK(l7, h7), o[1], 0, 0, 0);
	v_mfma_f32_32x32x16_bf16 v[66:81], v[238:241], v[242:245], v[66:81]
	v_mfma_f32_32x32x16_bf16 v[114:129], v[230:233], v[246:249], v[114:129]
	v_mfma_f32_32x32x16_bf16 v[66:81], v[234:237], v[246:249], v[66:81]
	v_exp_f32_e32 v82, v82
	v_exp_f32_e32 v83, v83
	v_exp_f32_e32 v84, v84
	v_exp_f32_e32 v85, v85
	v_exp_f32_e32 v86, v86
	v_exp_f32_e32 v87, v87
	v_exp_f32_e32 v88, v88
	v_exp_f32_e32 v89, v89
	v_add_f32_e32 v178, v168, v166
	v_add_f32_e32 v179, v175, v177
	v_add_f32_e32 v180, v169, v167
	v_add_f32_e32 v181, v174, v176
	v_exp_f32_e32 v90, v90
	v_exp_f32_e32 v91, v91
	v_exp_f32_e32 v92, v92
	v_exp_f32_e32 v93, v93
	v_add_f32_e32 v178, v170, v178
	v_add_f32_e32 v179, v173, v179
	v_add_f32_e32 v180, v165, v180
	v_add_f32_e32 v181, v171, v181
	v_exp_f32_e32 v94, v94
	v_exp_f32_e32 v95, v95
	v_exp_f32_e32 v96, v96
	v_exp_f32_e32 v97, v97
	v_add_f32_e32 v178, v163, v178
	v_add_f32_e32 v179, v172, v179
	v_add_f32_e32 v180, v162, v180
	v_add_f32_e32 v181, v164, v181
	v_add_f32_e32 v178, v82, v178
	v_add_f32_e32 v179, v179, v83
	v_add_f32_e32 v180, v180, v84
	v_add_f32_e32 v181, v181, v85
	v_add_f32_e32 v178, v86, v178
	v_add_f32_e32 v179, v87, v179
	v_add_f32_e32 v180, v88, v180
	v_add_f32_e32 v181, v89, v181
	v_add_f32_e32 v178, v90, v178
	v_add_f32_e32 v179, v91, v179
	v_add_f32_e32 v180, v92, v180
	v_add_f32_e32 v181, v93, v181
	v_add_f32_e32 v178, v94, v178
	v_add_f32_e32 v179, v95, v179
	v_add_f32_e32 v180, v96, v180
	v_add_f32_e32 v181, v97, v181
	v_add_f32_e32 v178, v178, v179
	v_add_f32_e32 v179, v180, v181
	v_add_f32_e32 v229, v178, v179
	v_mov_b32_e32 v230, v229
	v_cvt_pk_bf16_f32 v166, v166, v177
	v_cvt_pk_bf16_f32 v167, v167, v176
	v_cvt_pk_bf16_f32 v168, v168, v175
	v_cvt_pk_bf16_f32 v169, v169, v174
	s_nop 1
	v_permlane32_swap_b32_e32 v229, v230
	v_cvt_pk_bf16_f32 v170, v170, v173
	v_cvt_pk_bf16_f32 v171, v165, v171
	v_cvt_pk_bf16_f32 v172, v163, v172
	v_cvt_pk_bf16_f32 v173, v162, v164
	v_cvt_pk_bf16_f32 v174, v82, v83
	v_cvt_pk_bf16_f32 v175, v84, v85
	v_cvt_pk_bf16_f32 v176, v86, v87
	v_cvt_pk_bf16_f32 v177, v88, v89
	v_cvt_pk_bf16_f32 v178, v90, v91
	v_cvt_pk_bf16_f32 v179, v92, v93
	v_cvt_pk_bf16_f32 v180, v94, v95
	v_cvt_pk_bf16_f32 v181, v96, v97
	s_nop 0
	v_add_co_u32_e32 v86, vcc, s69, v190
	s_nop 1
	v_addc_co_u32_e32 v87, vcc, 0, v191, vcc
	v_add_co_u32_e32 v90, vcc, s74, v190
	s_nop 1
	v_addc_co_u32_e32 v91, vcc, 0, v191, vcc
	global_load_dwordx4 v[82:85], v[86:87], off offset:256
	s_nop 0
	global_load_dwordx4 v[86:89], v[86:87], off
	s_nop 0
	global_load_dwordx4 v[94:97], v[90:91], off offset:256
	s_nop 0
	global_load_dwordx4 v[90:93], v[90:91], off
	v_add_co_u32_e32 v162, vcc, s75, v196
	s_nop 1
	v_addc_co_u32_e32 v163, vcc, 0, v197, vcc
	global_load_dwordx4 v[162:165], v[162:163], off
	ds_read_b64_tr_b16 v[232:233], v208 offset:0
	ds_read_b64_tr_b16 v[234:235], v208 offset:0x800
	ds_read_b64_tr_b16 v[236:237], v208 offset:0x1000
	ds_read_b64_tr_b16 v[238:239], v208 offset:0x1800
	ds_read_b64_tr_b16 v[240:241], v208 offset:0x2000
	ds_read_b64_tr_b16 v[242:243], v208 offset:0x2800
	ds_read_b64_tr_b16 v[244:245], v208 offset:0x3000
	ds_read_b64_tr_b16 v[246:247], v208 offset:0x3800
	ds_read_b64_tr_b16 v[248:249], v208 offset:0x200
	ds_read_b64_tr_b16 v[250:251], v208 offset:0xa00
	s_waitcnt lgkmcnt(8)
	s_nop 0
	v_mfma_f32_32x32x16_bf16 v[2:17], v[166:169], v[232:235], v[2:17]
	ds_read_b64_tr_b16 v[232:233], v208 offset:0x1200
	ds_read_b64_tr_b16 v[234:235], v208 offset:0x1a00
	s_waitcnt lgkmcnt(8)
	v_mfma_f32_32x32x16_bf16 v[2:17], v[170:173], v[236:239], v[2:17]
	ds_read_b64_tr_b16 v[236:237], v208 offset:0x2200
	ds_read_b64_tr_b16 v[238:239], v208 offset:0x2a00
	s_waitcnt lgkmcnt(8)
	v_mfma_f32_32x32x16_bf16 v[2:17], v[174:177], v[240:243], v[2:17]
	ds_read_b64_tr_b16 v[240:241], v208 offset:0x3200
	ds_read_b64_tr_b16 v[242:243], v208 offset:0x3a00
	s_waitcnt lgkmcnt(8)
	v_mfma_f32_32x32x16_bf16 v[2:17], v[178:181], v[244:247], v[2:17]
	ds_read_b64_tr_b16 v[244:245], v208 offset:0x400
	ds_read_b64_tr_b16 v[246:247], v208 offset:0xc00
	s_waitcnt lgkmcnt(8)
	v_mfma_f32_32x32x16_bf16 v[50:65], v[166:169], v[248:251], v[50:65]
	ds_read_b64_tr_b16 v[248:249], v208 offset:0x1400
	ds_read_b64_tr_b16 v[250:251], v208 offset:0x1c00
	s_waitcnt lgkmcnt(8)
	v_mfma_f32_32x32x16_bf16 v[50:65], v[170:173], v[232:235], v[50:65]
	ds_read_b64_tr_b16 v[232:233], v208 offset:0x2400
	ds_read_b64_tr_b16 v[234:235], v208 offset:0x2c00
	s_waitcnt lgkmcnt(8)
	v_mfma_f32_32x32x16_bf16 v[50:65], v[174:177], v[236:239], v[50:65]
	ds_read_b64_tr_b16 v[236:237], v208 offset:0x3400
	ds_read_b64_tr_b16 v[238:239], v208 offset:0x3c00
	s_waitcnt lgkmcnt(8)
	v_mfma_f32_32x32x16_bf16 v[50:65], v[178:181], v[240:243], v[50:65]
	ds_read_b64_tr_b16 v[240:241], v208 offset:0x600
	ds_read_b64_tr_b16 v[242:243], v208 offset:0xe00
	s_waitcnt lgkmcnt(8)
	v_mfma_f32_32x32x16_bf16 v[34:49], v[166:169], v[244:247], v[34:49]
	ds_read_b64_tr_b16 v[244:245], v208 offset:0x1600
	ds_read_b64_tr_b16 v[246:247], v208 offset:0x1e00
	s_waitcnt lgkmcnt(8)
	v_mfma_f32_32x32x16_bf16 v[34:49], v[170:173], v[248:251], v[34:49]
	ds_read_b64_tr_b16 v[248:249], v208 offset:0x2600
	ds_read_b64_tr_b16 v[250:251], v208 offset:0x2e00
	s_waitcnt lgkmcnt(8)
	v_mfma_f32_32x32x16_bf16 v[34:49], v[174:177], v[232:235], v[34:49]
	ds_read_b64_tr_b16 v[232:233], v208 offset:0x3600
	ds_read_b64_tr_b16 v[234:235], v208 offset:0x3e00
	s_waitcnt lgkmcnt(8)
	v_mfma_f32_32x32x16_bf16 v[34:49], v[178:181], v[236:239], v[34:49]
	s_waitcnt lgkmcnt(6)
	v_mfma_f32_32x32x16_bf16 v[18:33], v[166:169], v[240:243], v[18:33]
	s_waitcnt lgkmcnt(4)
	v_mfma_f32_32x32x16_bf16 v[18:33], v[170:173], v[244:247], v[18:33]
	s_waitcnt lgkmcnt(2)
	v_mfma_f32_32x32x16_bf16 v[18:33], v[174:177], v[248:251], v[18:33]
	s_waitcnt lgkmcnt(0)
	v_max_f32_e32 v166, v114, v118
	v_max_f32_e32 v167, v115, v119
	v_max_f32_e32 v168, v117, v121
	v_max3_f32 v169, v116, v120, v124
	v_max3_f32 v168, v168, v125, v129
	v_max3_f32 v166, v166, v122, v126
	v_max3_f32 v167, v167, v123, v127
	v_max3_f32 v169, v169, v128, v68
	v_max3_f32 v168, v168, v69, v73
	v_max3_f32 v166, v166, v66, v70
	v_max3_f32 v167, v167, v67, v71
	v_max3_f32 v169, v169, v72, v76
	v_max3_f32 v168, v168, v77, v81
	v_mfma_f32_32x32x16_bf16 v[18:33], v[178:181], v[232:235], v[18:33]
	v_max3_f32 v166, v166, v74, v78
	v_max3_f32 v167, v167, v75, v79
	v_max3_f32 v168, v169, v80, v168
	v_max3_f32 v166, v166, v167, v168
	v_mov_b32_e32 v167, v166
	v_cmp_ge_f32_e32 vcc, s48, v167
	s_cmp_eq_u64 vcc, exec
	v_mov_b32_e32 v166, 1.0
	s_cbranch_scc0 .LBB0_401
	v_mov_b32_e32 v225, v227

; template <bool FIRST>
; __device__ __forceinline__ void partialSM(f32x16& p0, f32x16& p1, float& mC, float& alpha) {
;     ...
;   { auto rr = __builtin_amdgcn_permlane32_swap(__float_as_uint(pmax), __float_as_uint(pmax), false, false);
;     pmax = fmaxf(__uint_as_float(rr[0]), __uint_as_float(rr[1])); }
;   if (!FIRST && __builtin_expect(__all(pmax <= THR2), 1)) { alpha = 1.f; }
;   else { const float delta = FIRST ? fmaxf(pmax, -200.f) : fmaxf(pmax, 0.f); alpha = FIRST ? 1.f : __builtin_amdgcn_exp2f(-delta); mC += delta;
; #pragma unroll
;     for (int r = 0; r < 16; ++r) p0[r] -= delta;
; #pragma unroll
;     for (int r = 0; r < 16; ++r) p1[r] -= delta; }
.LBB0_400:
	v_mov_b32_e32 v167, v166
	s_nop 1
	v_permlane32_swap_b32_e32 v166, v167
	v_max_f32_e32 v166, v166, v167
	v_max_f32_e32 v166, v166, v166
	v_max_f32_e32 v166, 0, v166
	v_exp_f32_e64 v226, -v166
	v_add_f32_e32 v227, v225, v166
	v_pk_add_f32 v[114:115], v[114:115], v[166:167] op_sel_hi:[1,0] neg_lo:[0,1] neg_hi:[0,1]
	v_pk_add_f32 v[116:117], v[116:117], v[166:167] op_sel_hi:[1,0] neg_lo:[0,1] neg_hi:[0,1]
	v_pk_add_f32 v[118:119], v[118:119], v[166:167] op_sel_hi:[1,0] neg_lo:[0,1] neg_hi:[0,1]
	v_pk_add_f32 v[120:121], v[120:121], v[166:167] op_sel_hi:[1,0] neg_lo:[0,1] neg_hi:[0,1]
	v_pk_add_f32 v[122:123], v[122:123], v[166:167] op_sel_hi:[1,0] neg_lo:[0,1] neg_hi:[0,1]
	v_pk_add_f32 v[124:125], v[124:125], v[166:167] op_sel_hi:[1,0] neg_lo:[0,1] neg_hi:[0,1]
	v_pk_add_f32 v[126:127], v[126:127], v[166:167] op_sel_hi:[1,0] neg_lo:[0,1] neg_hi:[0,1]
	v_pk_add_f32 v[128:129], v[128:129], v[166:167] op_sel_hi:[1,0] neg_lo:[0,1] neg_hi:[0,1]
	v_sub_f32_e32 v97, v97, v166
	v_sub_f32_e32 v96, v96, v166
	v_sub_f32_e32 v95, v95, v166
	v_sub_f32_e32 v94, v94, v166
	v_sub_f32_e32 v93, v93, v166
	v_sub_f32_e32 v92, v92, v166
	v_sub_f32_e32 v91, v91, v166
	v_sub_f32_e32 v90, v90, v166
	v_sub_f32_e32 v89, v89, v166
	v_sub_f32_e32 v88, v88, v166
	v_sub_f32_e32 v87, v87, v166
	v_sub_f32_e32 v86, v86, v166
	v_sub_f32_e32 v85, v85, v166
	v_sub_f32_e32 v84, v84, v166
	v_sub_f32_e32 v83, v83, v166
	v_sub_f32_e32 v82, v82, v166
	s_branch .LBB0_388
.LBB0_401:
	v_mov_b32_e32 v166, v167
	s_nop 1
	v_permlane32_swap_b32_e32 v167, v166
	v_max_f32_e32 v167, v167, v166
	v_max_f32_e32 v166, v167, v167
	v_max_f32_e32 v168, 0, v166
	v_exp_f32_e64 v166, -v168
	v_add_f32_e32 v225, v227, v168
	v_pk_add_f32 v[114:115], v[114:115], v[168:169] op_sel_hi:[1,0] neg_lo:[0,1] neg_hi:[0,1]
	v_pk_add_f32 v[116:117], v[116:117], v[168:169] op_sel_hi:[1,0] neg_lo:[0,1] neg_hi:[0,1]
	v_pk_add_f32 v[118:119], v[118:119], v[168:169] op_sel_hi:[1,0] neg_lo:[0,1] neg_hi:[0,1]
	v_pk_add_f32 v[120:121], v[120:121], v[168:169] op_sel_hi:[1,0] neg_lo:[0,1] neg_hi:[0,1]
	v_pk_add_f32 v[122:123], v[122:123], v[168:169] op_sel_hi:[1,0] neg_lo:[0,1] neg_hi:[0,1]
	v_pk_add_f32 v[124:125], v[124:125], v[168:169] op_sel_hi:[1,0] neg_lo:[0,1] neg_hi:[0,1]
	v_pk_add_f32 v[126:127], v[126:127], v[168:169] op_sel_hi:[1,0] neg_lo:[0,1] neg_hi:[0,1]
	v_pk_add_f32 v[128:129], v[128:129], v[168:169] op_sel_hi:[1,0] neg_lo:[0,1] neg_hi:[0,1]
	v_sub_f32_e32 v81, v81, v168
	v_sub_f32_e32 v80, v80, v168
	v_sub_f32_e32 v79, v79, v168
	v_sub_f32_e32 v78, v78, v168
	v_sub_f32_e32 v77, v77, v168
	v_sub_f32_e32 v76, v76, v168
	v_sub_f32_e32 v75, v75, v168
	v_sub_f32_e32 v74, v74, v168
	v_sub_f32_e32 v73, v73, v168
	v_sub_f32_e32 v72, v72, v168
	v_sub_f32_e32 v71, v71, v168
	v_sub_f32_e32 v70, v70, v168
	v_sub_f32_e32 v69, v69, v168
	v_sub_f32_e32 v68, v68, v168
	v_sub_f32_e32 v67, v67, v168
	v_sub_f32_e32 v66, v66, v168
	s_branch .LBB0_394

; __device__ __forceinline__ void qkt8_roll(f32x16& p0, f32x16& p1, const f32x16& negm, int kb, const bf16x8* qr) {
;   const int a0 = kb ^ (0 << 5); const bf16x8 x0 = lds_rd128<0>(a0), y0 = lds_rd128<8192>(a0);
;   const int a1 = kb ^ (1 << 5); const bf16x8 x1 = lds_rd128<0>(a1), y1 = lds_rd128<8192>(a1);
;   const int a2 = kb ^ (2 << 5); const bf16x8 x2 = lds_rd128<0>(a2), y2 = lds_rd128<8192>(a2);
;   asm volatile("s_waitcnt lgkmcnt(4)" ::: "memory"); SBAR_M();
;   p0 = __builtin_amdgcn_mfma_f32_32x32x16_bf16(x0, qr[0], negm, 0, 0, 0); p1 = __builtin_amdgcn_mfma_f32_32x32x16_bf16(y0, qr[0], negm, 0, 0, 0);
;   const int a3 = kb ^ (3 << 5); const bf16x8 x3 = lds_rd128<0>(a3), y3 = lds_rd128<8192>(a3);
;   asm volatile("s_waitcnt lgkmcnt(4)" ::: "memory"); SBAR_M();
;   p0 = __builtin_amdgcn_mfma_f32_32x32x16_bf16(x1, qr[1], p0, 0, 0, 0); p1 = __builtin_amdgcn_mfma_f32_32x32x16_bf16(y1, qr[1], p1, 0, 0, 0);
;   const int a4 = kb ^ (4 << 5); const bf16x8 x4 = lds_rd128<0>(a4), y4 = lds_rd128<8192>(a4);
;   asm volatile("s_waitcnt lgkmcnt(4)" ::: "memory"); SBAR_M();
;   p0 = __builtin_amdgcn_mfma_f32_32x32x16_bf16(x2, qr[2], p0, 0, 0, 0); p1 = __builtin_amdgcn_mfma_f32_32x32x16_bf16(y2, qr[2], p1, 0, 0, 0);
;   const int a5 = kb ^ (5 << 5); const bf16x8 x5 = lds_rd128<0>(a5), y5 = lds_rd128<8192>(a5);
;   asm volatile("s_waitcnt lgkmcnt(4)" ::: "memory"); SBAR_M();
;   p0 = __builtin_amdgcn_mfma_f32_32x32x16_bf16(x3, qr[3], p0, 0, 0, 0); p1 = __builtin_amdgcn_mfma_f32_32x32x16_bf16(y3, qr[3], p1, 0, 0, 0);
;   const int a6 = kb ^ (6 << 5); const bf16x8 x6 = lds_rd128<0>(a6), y6 = lds_rd128<8192>(a6);
;   asm volatile("s_waitcnt lgkmcnt(4)" ::: "memory"); SBAR_M();
;   p0 = __builtin_amdgcn_mfma_f32_32x32x16_bf16(x4, qr[4], p0, 0, 0, 0); p1 = __builtin_amdgcn_mfma_f32_32x32x16_bf16(y4, qr[4], p1, 0, 0, 0);
;   const int a7 = kb ^ (7 << 5); const bf16x8 x7 = lds_rd128<0>(a7), y7 = lds_rd128<8192>(a7);
;   asm volatile("s_waitcnt lgkmcnt(4)" ::: "memory"); SBAR_M();
;   p0 = __builtin_amdgcn_mfma_f32_32x32x16_bf16(x5, qr[5], p0, 0, 0, 0); p1 = __builtin_amdgcn_mfma_f32_32x32x16_bf16(y5, qr[5], p1, 0, 0, 0);
;   asm volatile("s_waitcnt lgkmcnt(2)" ::: "memory"); SBAR_M();
;   p0 = __builtin_amdgcn_mfma_f32_32x32x16_bf16(x6, qr[6], p0, 0, 0, 0); p1 = __builtin_amdgcn_mfma_f32_32x32x16_bf16(y6, qr[6], p1, 0, 0, 0);
.LBB0_421:
	v_exp_f32_e32 v66, v66
	v_exp_f32_e32 v67, v67
	v_exp_f32_e32 v68, v68
	v_exp_f32_e32 v69, v69
	v_exp_f32_e32 v70, v70
	v_exp_f32_e32 v71, v71
	v_exp_f32_e32 v72, v72
	v_exp_f32_e32 v73, v73
	v_add_f32_e32 v98, v148, v146
	v_add_f32_e32 v99, v159, v161
	v_add_f32_e32 v100, v149, v147
	v_add_f32_e32 v101, v158, v160
	v_exp_f32_e32 v74, v74
	v_exp_f32_e32 v75, v75
	v_exp_f32_e32 v76, v76
	v_exp_f32_e32 v77, v77
	v_add_f32_e32 v98, v150, v98
	v_add_f32_e32 v99, v157, v99
	v_add_f32_e32 v100, v151, v100
	v_add_f32_e32 v101, v156, v101
	v_exp_f32_e32 v78, v78
	v_exp_f32_e32 v79, v79
	v_exp_f32_e32 v80, v80
	v_exp_f32_e32 v81, v81
	v_add_f32_e32 v98, v152, v98
	v_add_f32_e32 v99, v155, v99
	v_add_f32_e32 v100, v153, v100
	v_add_f32_e32 v101, v154, v101
	v_add_f32_e32 v98, v66, v98
	v_add_f32_e32 v99, v67, v99
	v_add_f32_e32 v100, v68, v100
	v_add_f32_e32 v101, v69, v101
	v_add_f32_e32 v98, v70, v98
	v_add_f32_e32 v99, v71, v99
	v_add_f32_e32 v100, v72, v100
	v_add_f32_e32 v101, v73, v101
	v_add_f32_e32 v98, v74, v98
	v_add_f32_e32 v99, v75, v99
	v_add_f32_e32 v100, v76, v100
	v_add_f32_e32 v101, v77, v101
	v_add_f32_e32 v98, v78, v98
	v_add_f32_e32 v99, v79, v99
	v_add_f32_e32 v100, v80, v100
	v_add_f32_e32 v101, v81, v101
	v_add_f32_e32 v98, v98, v99
	v_add_f32_e32 v99, v100, v101
	v_add_f32_e32 v228, v98, v99
	v_mov_b32_e32 v229, v228
	v_cvt_pk_bf16_f32 v146, v146, v161
	v_cvt_pk_bf16_f32 v147, v147, v160
	v_cvt_pk_bf16_f32 v148, v148, v159
	v_cvt_pk_bf16_f32 v149, v149, v158
	v_cvt_pk_bf16_f32 v150, v150, v157
	v_cvt_pk_bf16_f32 v151, v151, v156
	v_cvt_pk_bf16_f32 v152, v152, v155
	v_cvt_pk_bf16_f32 v153, v153, v154
	v_cvt_pk_bf16_f32 v158, v66, v67
	v_cvt_pk_bf16_f32 v159, v68, v69
	v_cvt_pk_bf16_f32 v160, v70, v71
	v_cvt_pk_bf16_f32 v161, v72, v73
	v_cvt_pk_bf16_f32 v154, v74, v75
	v_cvt_pk_bf16_f32 v155, v76, v77
	v_cvt_pk_bf16_f32 v156, v78, v79
	v_cvt_pk_bf16_f32 v157, v80, v81
	s_nop 1
	v_permlane32_swap_b32_e32 v228, v229
	v_cmp_neq_f32_e64 s[6:7], v232, -v227
	s_cmp_eq_u64 s[6:7], 0
	s_cselect_b64 s[6:7], -1, 0
	v_cndmask_b32_e64 v81, -v227, v97, s[6:7]
	v_cndmask_b32_e64 v80, -v227, v96, s[6:7]
	v_cndmask_b32_e64 v79, -v227, v95, s[6:7]
	v_cndmask_b32_e64 v78, -v227, v94, s[6:7]
	v_cndmask_b32_e64 v77, -v227, v93, s[6:7]
	v_cndmask_b32_e64 v76, -v227, v92, s[6:7]
	v_cndmask_b32_e64 v75, -v227, v91, s[6:7]
	v_cndmask_b32_e64 v74, -v227, v90, s[6:7]
	v_cndmask_b32_e64 v73, -v227, v89, s[6:7]
	v_cndmask_b32_e64 v72, -v227, v88, s[6:7]
	v_cndmask_b32_e64 v71, -v227, v87, s[6:7]
	v_cndmask_b32_e64 v70, -v227, v86, s[6:7]
	v_cndmask_b32_e64 v69, -v227, v85, s[6:7]
	v_cndmask_b32_e64 v68, -v227, v84, s[6:7]
	v_cndmask_b32_e64 v67, -v227, v83, s[6:7]
	v_cndmask_b32_e64 v66, -v227, v82, s[6:7]
	ds_read_b128 v[82:85], v224 offset:0
	ds_read_b128 v[162:165], v224 offset:0x2000
	ds_read_b128 v[166:169], v223 offset:0
	ds_read_b128 v[170:173], v223 offset:0x2000
	ds_read_b128 v[174:177], v222 offset:0
	ds_read_b128 v[188:191], v222 offset:0x2000
	s_waitcnt lgkmcnt(4)
	s_nop 1
	v_mfma_f32_32x32x16_bf16 v[98:113], v[82:85], v[142:145], v[66:81]
	v_mfma_f32_32x32x16_bf16 v[82:97], v[162:165], v[142:145], v[66:81]
	ds_read_b128 v[162:165], v221 offset:0
	ds_read_b128 v[192:195], v221 offset:0x2000
	s_waitcnt lgkmcnt(4)
	v_mfma_f32_32x32x16_bf16 v[98:113], v[166:169], v[138:141], v[98:113]
	ds_read_b128 v[166:169], v220 offset:0
	v_mfma_f32_32x32x16_bf16 v[82:97], v[170:173], v[138:141], v[82:97]
	ds_read_b128 v[170:173], v220 offset:0x2000
	s_waitcnt lgkmcnt(4)
	v_mfma_f32_32x32x16_bf16 v[98:113], v[174:177], v[134:137], v[98:113]
	ds_read_b128 v[174:177], v219 offset:0
	v_mfma_f32_32x32x16_bf16 v[82:97], v[188:191], v[134:137], v[82:97]
	ds_read_b128 v[188:191], v219 offset:0x2000
	s_waitcnt lgkmcnt(4)
	v_mfma_f32_32x32x16_bf16 v[98:113], v[162:165], v[130:133], v[98:113]
	ds_read_b128 v[162:165], v218 offset:0
	v_mfma_f32_32x32x16_bf16 v[82:97], v[192:195], v[130:133], v[82:97]
	ds_read_b128 v[192:195], v218 offset:0x2000
	s_waitcnt lgkmcnt(4)
	v_mfma_f32_32x32x16_bf16 v[98:113], v[166:169], v[126:129], v[98:113]
	ds_read_b128 v[166:169], v217 offset:0
	v_mfma_f32_32x32x16_bf16 v[82:97], v[170:173], v[126:129], v[82:97]
	ds_read_b128 v[170:173], v217 offset:0x2000
	s_waitcnt lgkmcnt(4)
	v_mfma_f32_32x32x16_bf16 v[98:113], v[174:177], v[122:125], v[98:113]
	s_waitcnt lgkmcnt(2)
	v_mfma_f32_32x32x16_bf16 v[82:97], v[188:191], v[122:125], v[82:97]
	v_mfma_f32_32x32x16_bf16 v[98:113], v[162:165], v[118:121], v[98:113]
	s_waitcnt lgkmcnt(0)
	v_mfma_f32_32x32x16_bf16 v[82:97], v[192:195], v[118:121], v[82:97]
	v_mfma_f32_32x32x16_bf16 v[98:113], v[166:169], v[114:117], v[98:113]
	v_mfma_f32_32x32x16_bf16 v[82:97], v[170:173], v[114:117], v[82:97]
	s_nop 10
	v_max_f32_e32 v162, v98, v102
	v_max_f32_e32 v163, v99, v103
	v_max_f32_e32 v164, v101, v105
	v_max3_f32 v165, v100, v104, v108
	v_max3_f32 v164, v164, v109, v113
	v_max3_f32 v162, v162, v106, v110
	v_max3_f32 v163, v163, v107, v111
	v_max3_f32 v165, v165, v112, v84
	v_max3_f32 v164, v164, v85, v89
	v_max3_f32 v162, v162, v82, v86
	v_max3_f32 v163, v163, v83, v87
	v_max3_f32 v165, v165, v88, v92
	v_max3_f32 v164, v164, v93, v97
	v_max3_f32 v162, v162, v90, v94
	v_max3_f32 v163, v163, v91, v95
	v_max3_f32 v164, v165, v96, v164
	v_max3_f32 v162, v162, v163, v164
	v_cmp_ge_f32_e32 vcc, s48, v162
	s_cmp_eq_u64 vcc, exec
	s_cbranch_scc0 .LBB0_435
	v_mov_b32_e32 v231, v227
	v_mov_b32_e32 v230, 1.0

; __device__ __forceinline__ void qkt8_roll(f32x16& p0, f32x16& p1, const f32x16& negm, int kb, const bf16x8* qr) {
;   const int a0 = kb ^ (0 << 5); const bf16x8 x0 = lds_rd128<0>(a0), y0 = lds_rd128<8192>(a0);
;   const int a1 = kb ^ (1 << 5); const bf16x8 x1 = lds_rd128<0>(a1), y1 = lds_rd128<8192>(a1);
;   const int a2 = kb ^ (2 << 5); const bf16x8 x2 = lds_rd128<0>(a2), y2 = lds_rd128<8192>(a2);
;   asm volatile("s_waitcnt lgkmcnt(4)" ::: "memory"); SBAR_M();
;   p0 = __builtin_amdgcn_mfma_f32_32x32x16_bf16(x0, qr[0], negm, 0, 0, 0); p1 = __builtin_amdgcn_mfma_f32_32x32x16_bf16(y0, qr[0], negm, 0, 0, 0);
;   const int a3 = kb ^ (3 << 5); const bf16x8 x3 = lds_rd128<0>(a3), y3 = lds_rd128<8192>(a3);
;   asm volatile("s_waitcnt lgkmcnt(4)" ::: "memory"); SBAR_M();
;   p0 = __builtin_amdgcn_mfma_f32_32x32x16_bf16(x1, qr[1], p0, 0, 0, 0); p1 = __builtin_amdgcn_mfma_f32_32x32x16_bf16(y1, qr[1], p1, 0, 0, 0);
;   const int a4 = kb ^ (4 << 5); const bf16x8 x4 = lds_rd128<0>(a4), y4 = lds_rd128<8192>(a4);
;   asm volatile("s_waitcnt lgkmcnt(4)" ::: "memory"); SBAR_M();
;   p0 = __builtin_amdgcn_mfma_f32_32x32x16_bf16(x2, qr[2], p0, 0, 0, 0); p1 = __builtin_amdgcn_mfma_f32_32x32x16_bf16(y2, qr[2], p1, 0, 0, 0);
;   const int a5 = kb ^ (5 << 5); const bf16x8 x5 = lds_rd128<0>(a5), y5 = lds_rd128<8192>(a5);
;   asm volatile("s_waitcnt lgkmcnt(4)" ::: "memory"); SBAR_M();
;   p0 = __builtin_amdgcn_mfma_f32_32x32x16_bf16(x3, qr[3], p0, 0, 0, 0); p1 = __builtin_amdgcn_mfma_f32_32x32x16_bf16(y3, qr[3], p1, 0, 0, 0);
;   const int a6 = kb ^ (6 << 5); const bf16x8 x6 = lds_rd128<0>(a6), y6 = lds_rd128<8192>(a6);
;   asm volatile("s_waitcnt lgkmcnt(4)" ::: "memory"); SBAR_M();
;   p0 = __builtin_amdgcn_mfma_f32_32x32x16_bf16(x4, qr[4], p0, 0, 0, 0); p1 = __builtin_amdgcn_mfma_f32_32x32x16_bf16(y4, qr[4], p1, 0, 0, 0);
;   const int a7 = kb ^ (7 << 5); const bf16x8 x7 = lds_rd128<0>(a7), y7 = lds_rd128<8192>(a7);
;   asm volatile("s_waitcnt lgkmcnt(4)" ::: "memory"); SBAR_M();
;   p0 = __builtin_amdgcn_mfma_f32_32x32x16_bf16(x5, qr[5], p0, 0, 0, 0); p1 = __builtin_amdgcn_mfma_f32_32x32x16_bf16(y5, qr[5], p1, 0, 0, 0);
;   asm volatile("s_waitcnt lgkmcnt(2)" ::: "memory"); SBAR_M();
;   p0 = __builtin_amdgcn_mfma_f32_32x32x16_bf16(x6, qr[6], p0, 0, 0, 0); p1 = __builtin_amdgcn_mfma_f32_32x32x16_bf16(y6, qr[6], p1, 0, 0, 0);
.LBB0_427:
	v_exp_f32_e32 v146, v98
	v_exp_f32_e32 v153, v99
	v_exp_f32_e32 v147, v100
	v_exp_f32_e32 v152, v101
	v_exp_f32_e32 v148, v102
	v_exp_f32_e32 v151, v103
	v_exp_f32_e32 v149, v104
	v_exp_f32_e32 v150, v105
	v_exp_f32_e32 v103, v106
	v_exp_f32_e32 v105, v107
	v_exp_f32_e32 v101, v108
	v_exp_f32_e32 v104, v109
	v_exp_f32_e32 v99, v110
	v_exp_f32_e32 v102, v111
	v_exp_f32_e32 v98, v112
	v_exp_f32_e32 v100, v113
	v_xor_b32_e32 v106, 0x80000000, v227
	v_exp_f32_e32 v82, v82
	v_exp_f32_e32 v83, v83
	v_exp_f32_e32 v84, v84
	v_exp_f32_e32 v85, v85
	v_cndmask_b32_e64 v232, v106, v232, s[6:7]
	v_exp_f32_e32 v86, v86
	v_exp_f32_e32 v87, v87
	v_exp_f32_e32 v88, v88
	v_exp_f32_e32 v89, v89
	v_add_f32_e32 v106, v148, v146
	v_add_f32_e32 v107, v151, v153
	v_add_f32_e32 v108, v149, v147
	v_add_f32_e32 v109, v150, v152
	v_exp_f32_e32 v90, v90
	v_exp_f32_e32 v91, v91
	v_exp_f32_e32 v92, v92
	v_exp_f32_e32 v93, v93
	v_add_f32_e32 v106, v103, v106
	v_add_f32_e32 v107, v105, v107
	v_add_f32_e32 v108, v101, v108
	v_add_f32_e32 v109, v104, v109
	v_exp_f32_e32 v94, v94
	v_exp_f32_e32 v95, v95
	v_exp_f32_e32 v96, v96
	v_exp_f32_e32 v97, v97
	v_add_f32_e32 v106, v99, v106
	v_add_f32_e32 v107, v102, v107
	v_add_f32_e32 v108, v98, v108
	v_add_f32_e32 v109, v100, v109
	v_add_f32_e32 v106, v82, v106
	v_add_f32_e32 v107, v107, v83
	v_add_f32_e32 v108, v108, v84
	v_add_f32_e32 v109, v109, v85
	v_add_f32_e32 v106, v86, v106
	v_add_f32_e32 v107, v87, v107
	v_add_f32_e32 v108, v88, v108
	v_add_f32_e32 v109, v89, v109
	v_add_f32_e32 v106, v90, v106
	v_add_f32_e32 v107, v91, v107
	v_add_f32_e32 v108, v92, v108
	v_add_f32_e32 v109, v93, v109
	v_add_f32_e32 v106, v94, v106
	v_add_f32_e32 v107, v95, v107
	v_add_f32_e32 v108, v96, v108
	v_add_f32_e32 v109, v97, v109
	v_add_f32_e32 v106, v106, v107
	v_add_f32_e32 v107, v108, v109
	v_add_f32_e32 v233, v106, v107
	s_waitcnt lgkmcnt(0)
	s_barrier
	v_mov_b32_e32 v234, v233
	v_cvt_pk_bf16_f32 v146, v146, v153
	v_cvt_pk_bf16_f32 v147, v147, v152
	v_cvt_pk_bf16_f32 v148, v148, v151
	v_cvt_pk_bf16_f32 v149, v149, v150
	v_cvt_pk_bf16_f32 v150, v103, v105
	v_cvt_pk_bf16_f32 v151, v101, v104
	v_cvt_pk_bf16_f32 v152, v99, v102
	v_cvt_pk_bf16_f32 v153, v98, v100
	v_cvt_pk_bf16_f32 v158, v82, v83
	v_cvt_pk_bf16_f32 v159, v84, v85
	v_cvt_pk_bf16_f32 v160, v86, v87
	v_cvt_pk_bf16_f32 v161, v88, v89
	v_cvt_pk_bf16_f32 v154, v90, v91
	v_cvt_pk_bf16_f32 v155, v92, v93
	v_cvt_pk_bf16_f32 v156, v94, v95
	v_cvt_pk_bf16_f32 v157, v96, v97
	s_nop 1
	v_permlane32_swap_b32_e32 v233, v234
	v_cmp_neq_f32_e64 s[6:7], v232, -v231
	s_cmp_eq_u64 s[6:7], 0
	s_cselect_b64 s[6:7], -1, 0
	v_cndmask_b32_e64 v97, -v231, v81, s[6:7]
	v_cndmask_b32_e64 v96, -v231, v80, s[6:7]
	v_cndmask_b32_e64 v95, -v231, v79, s[6:7]
	v_cndmask_b32_e64 v94, -v231, v78, s[6:7]
	v_cndmask_b32_e64 v93, -v231, v77, s[6:7]
	v_cndmask_b32_e64 v92, -v231, v76, s[6:7]
	v_cndmask_b32_e64 v91, -v231, v75, s[6:7]
	v_cndmask_b32_e64 v90, -v231, v74, s[6:7]
	v_cndmask_b32_e64 v89, -v231, v73, s[6:7]
	v_cndmask_b32_e64 v88, -v231, v72, s[6:7]
	v_cndmask_b32_e64 v87, -v231, v71, s[6:7]
	v_cndmask_b32_e64 v86, -v231, v70, s[6:7]
	v_cndmask_b32_e64 v85, -v231, v69, s[6:7]
	v_cndmask_b32_e64 v84, -v231, v68, s[6:7]
	v_cndmask_b32_e64 v83, -v231, v67, s[6:7]
	v_cndmask_b32_e64 v82, -v231, v66, s[6:7]
	ds_read_b128 v[66:69], v200 offset:0
	ds_read_b128 v[162:165], v200 offset:0x2000
	ds_read_b128 v[166:169], v210 offset:0
	ds_read_b128 v[170:173], v210 offset:0x2000
	ds_read_b128 v[174:177], v211 offset:0
	ds_read_b128 v[192:195], v211 offset:0x2000
	s_waitcnt lgkmcnt(4)
	s_nop 1
	v_mfma_f32_32x32x16_bf16 v[98:113], v[66:69], v[142:145], v[82:97]
	v_mfma_f32_32x32x16_bf16 v[66:81], v[162:165], v[142:145], v[82:97]
	ds_read_b128 v[162:165], v212 offset:0
	ds_read_b128 v[236:239], v212 offset:0x2000
	s_waitcnt lgkmcnt(4)
	v_mfma_f32_32x32x16_bf16 v[98:113], v[166:169], v[138:141], v[98:113]
	ds_read_b128 v[166:169], v213 offset:0
	v_mfma_f32_32x32x16_bf16 v[66:81], v[170:173], v[138:141], v[66:81]
	ds_read_b128 v[170:173], v213 offset:0x2000
	s_waitcnt lgkmcnt(4)
	v_mfma_f32_32x32x16_bf16 v[98:113], v[174:177], v[134:137], v[98:113]
	ds_read_b128 v[174:177], v214 offset:0
	v_mfma_f32_32x32x16_bf16 v[66:81], v[192:195], v[134:137], v[66:81]
	ds_read_b128 v[192:195], v214 offset:0x2000
	s_waitcnt lgkmcnt(4)
	v_mfma_f32_32x32x16_bf16 v[98:113], v[162:165], v[130:133], v[98:113]
	ds_read_b128 v[162:165], v215 offset:0
	v_mfma_f32_32x32x16_bf16 v[66:81], v[236:239], v[130:133], v[66:81]
	ds_read_b128 v[236:239], v215 offset:0x2000
	s_waitcnt lgkmcnt(4)
	v_mfma_f32_32x32x16_bf16 v[98:113], v[166:169], v[126:129], v[98:113]
	ds_read_b128 v[166:169], v216 offset:0
	v_mfma_f32_32x32x16_bf16 v[66:81], v[170:173], v[126:129], v[66:81]
	ds_read_b128 v[170:173], v216 offset:0x2000
	s_waitcnt lgkmcnt(4)
	v_mfma_f32_32x32x16_bf16 v[98:113], v[174:177], v[122:125], v[98:113]
	s_waitcnt lgkmcnt(2)
	v_mfma_f32_32x32x16_bf16 v[66:81], v[192:195], v[122:125], v[66:81]
	v_mfma_f32_32x32x16_bf16 v[98:113], v[162:165], v[118:121], v[98:113]
	s_waitcnt lgkmcnt(0)
	v_mfma_f32_32x32x16_bf16 v[66:81], v[236:239], v[118:121], v[66:81]
	v_mfma_f32_32x32x16_bf16 v[98:113], v[166:169], v[114:117], v[98:113]
	v_mfma_f32_32x32x16_bf16 v[66:81], v[170:173], v[114:117], v[66:81]
	s_nop 10
	v_max_f32_e32 v162, v98, v102
	v_max_f32_e32 v163, v99, v103
	v_max_f32_e32 v164, v101, v105
	v_max3_f32 v165, v100, v104, v108
	v_max3_f32 v164, v164, v109, v113
	v_max3_f32 v162, v162, v106, v110
	v_max3_f32 v163, v163, v107, v111
	v_max3_f32 v165, v165, v112, v68
	v_max3_f32 v164, v164, v69, v73
	v_max3_f32 v162, v162, v66, v70
	v_max3_f32 v163, v163, v67, v71
	v_max3_f32 v165, v165, v72, v76
	v_max3_f32 v164, v164, v77, v81
	v_max3_f32 v162, v162, v74, v78
	v_max3_f32 v163, v163, v75, v79
	v_max3_f32 v164, v165, v80, v164
	v_max3_f32 v162, v162, v163, v164
	v_cmp_ge_f32_e32 vcc, s48, v162
	s_cmp_eq_u64 vcc, exec
	v_mov_b32_e32 v226, 1.0
	s_cbranch_scc0 .LBB0_436
	v_mov_b32_e32 v227, v231

; template <bool FIRST>
; __device__ __forceinline__ void partialSM(f32x16& p0, f32x16& p1, float& mC, float& alpha) {
;     ...
;   { auto rr = __builtin_amdgcn_permlane32_swap(__float_as_uint(pmax), __float_as_uint(pmax), false, false);
;     pmax = fmaxf(__uint_as_float(rr[0]), __uint_as_float(rr[1])); }
;   if (!FIRST && __builtin_expect(__all(pmax <= THR2), 1)) { alpha = 1.f; }
;   else { const float delta = FIRST ? fmaxf(pmax, -200.f) : fmaxf(pmax, 0.f); alpha = FIRST ? 1.f : __builtin_amdgcn_exp2f(-delta); mC += delta;
; #pragma unroll
;     for (int r = 0; r < 16; ++r) p0[r] -= delta;
; #pragma unroll
;     for (int r = 0; r < 16; ++r) p1[r] -= delta; }
.LBB0_435:
	v_mov_b32_e32 v163, v162
	s_nop 1
	v_permlane32_swap_b32_e32 v162, v163
	v_max_f32_e32 v162, v162, v163
	v_max_f32_e32 v162, v162, v162
	v_max_f32_e32 v162, 0, v162
	v_exp_f32_e64 v230, -v162
	v_add_f32_e32 v231, v227, v162
	v_pk_add_f32 v[98:99], v[98:99], v[162:163] op_sel_hi:[1,0] neg_lo:[0,1] neg_hi:[0,1]
	v_pk_add_f32 v[100:101], v[100:101], v[162:163] op_sel_hi:[1,0] neg_lo:[0,1] neg_hi:[0,1]
	v_pk_add_f32 v[102:103], v[102:103], v[162:163] op_sel_hi:[1,0] neg_lo:[0,1] neg_hi:[0,1]
	v_pk_add_f32 v[104:105], v[104:105], v[162:163] op_sel_hi:[1,0] neg_lo:[0,1] neg_hi:[0,1]
	v_pk_add_f32 v[106:107], v[106:107], v[162:163] op_sel_hi:[1,0] neg_lo:[0,1] neg_hi:[0,1]
	v_pk_add_f32 v[108:109], v[108:109], v[162:163] op_sel_hi:[1,0] neg_lo:[0,1] neg_hi:[0,1]
	v_pk_add_f32 v[110:111], v[110:111], v[162:163] op_sel_hi:[1,0] neg_lo:[0,1] neg_hi:[0,1]
	v_pk_add_f32 v[112:113], v[112:113], v[162:163] op_sel_hi:[1,0] neg_lo:[0,1] neg_hi:[0,1]
	v_sub_f32_e32 v97, v97, v162
	v_sub_f32_e32 v96, v96, v162
	v_sub_f32_e32 v95, v95, v162
	v_sub_f32_e32 v94, v94, v162
	v_sub_f32_e32 v93, v93, v162
	v_sub_f32_e32 v92, v92, v162
	v_sub_f32_e32 v91, v91, v162
	v_sub_f32_e32 v90, v90, v162
	v_sub_f32_e32 v89, v89, v162
	v_sub_f32_e32 v88, v88, v162
	v_sub_f32_e32 v87, v87, v162
	v_sub_f32_e32 v86, v86, v162
	v_sub_f32_e32 v85, v85, v162
	v_sub_f32_e32 v84, v84, v162
	v_sub_f32_e32 v83, v83, v162
	v_sub_f32_e32 v82, v82, v162
	s_branch .LBB0_423
.LBB0_436:
	v_mov_b32_e32 v163, v162
	s_nop 1
	v_permlane32_swap_b32_e32 v162, v163
	v_max_f32_e32 v162, v162, v163
	v_max_f32_e32 v162, v162, v162
	v_max_f32_e32 v162, 0, v162
	v_exp_f32_e64 v226, -v162
	v_add_f32_e32 v227, v231, v162
	v_pk_add_f32 v[98:99], v[98:99], v[162:163] op_sel_hi:[1,0] neg_lo:[0,1] neg_hi:[0,1]
	v_pk_add_f32 v[100:101], v[100:101], v[162:163] op_sel_hi:[1,0] neg_lo:[0,1] neg_hi:[0,1]
	v_pk_add_f32 v[102:103], v[102:103], v[162:163] op_sel_hi:[1,0] neg_lo:[0,1] neg_hi:[0,1]
	v_pk_add_f32 v[104:105], v[104:105], v[162:163] op_sel_hi:[1,0] neg_lo:[0,1] neg_hi:[0,1]
	v_pk_add_f32 v[106:107], v[106:107], v[162:163] op_sel_hi:[1,0] neg_lo:[0,1] neg_hi:[0,1]
	v_pk_add_f32 v[108:109], v[108:109], v[162:163] op_sel_hi:[1,0] neg_lo:[0,1] neg_hi:[0,1]
	v_pk_add_f32 v[110:111], v[110:111], v[162:163] op_sel_hi:[1,0] neg_lo:[0,1] neg_hi:[0,1]
	v_pk_add_f32 v[112:113], v[112:113], v[162:163] op_sel_hi:[1,0] neg_lo:[0,1] neg_hi:[0,1]
	v_sub_f32_e32 v81, v81, v162
	v_sub_f32_e32 v80, v80, v162
	v_sub_f32_e32 v79, v79, v162
	v_sub_f32_e32 v78, v78, v162
	v_sub_f32_e32 v77, v77, v162
	v_sub_f32_e32 v76, v76, v162
	v_sub_f32_e32 v75, v75, v162
	v_sub_f32_e32 v74, v74, v162
	v_sub_f32_e32 v73, v73, v162
	v_sub_f32_e32 v72, v72, v162
	v_sub_f32_e32 v71, v71, v162
	v_sub_f32_e32 v70, v70, v162
	v_sub_f32_e32 v69, v69, v162
	v_sub_f32_e32 v68, v68, v162
	v_sub_f32_e32 v67, v67, v162
	v_sub_f32_e32 v66, v66, v162
	s_branch .LBB0_429

; __device__ __forceinline__ void qkt8_roll(f32x16& p0, f32x16& p1, const f32x16& negm, int kb, const bf16x8* qr) {
;   const int a0 = kb ^ (0 << 5); const bf16x8 x0 = lds_rd128<0>(a0), y0 = lds_rd128<8192>(a0);
;   const int a1 = kb ^ (1 << 5); const bf16x8 x1 = lds_rd128<0>(a1), y1 = lds_rd128<8192>(a1);
;   const int a2 = kb ^ (2 << 5); const bf16x8 x2 = lds_rd128<0>(a2), y2 = lds_rd128<8192>(a2);
;   asm volatile("s_waitcnt lgkmcnt(4)" ::: "memory"); SBAR_M();
;   p0 = __builtin_amdgcn_mfma_f32_32x32x16_bf16(x0, qr[0], negm, 0, 0, 0); p1 = __builtin_amdgcn_mfma_f32_32x32x16_bf16(y0, qr[0], negm, 0, 0, 0);
;   const int a3 = kb ^ (3 << 5); const bf16x8 x3 = lds_rd128<0>(a3), y3 = lds_rd128<8192>(a3);
;   asm volatile("s_waitcnt lgkmcnt(4)" ::: "memory"); SBAR_M();
;   p0 = __builtin_amdgcn_mfma_f32_32x32x16_bf16(x1, qr[1], p0, 0, 0, 0); p1 = __builtin_amdgcn_mfma_f32_32x32x16_bf16(y1, qr[1], p1, 0, 0, 0);
;   const int a4 = kb ^ (4 << 5); const bf16x8 x4 = lds_rd128<0>(a4), y4 = lds_rd128<8192>(a4);
;   asm volatile("s_waitcnt lgkmcnt(4)" ::: "memory"); SBAR_M();
;   p0 = __builtin_amdgcn_mfma_f32_32x32x16_bf16(x2, qr[2], p0, 0, 0, 0); p1 = __builtin_amdgcn_mfma_f32_32x32x16_bf16(y2, qr[2], p1, 0, 0, 0);
;   const int a5 = kb ^ (5 << 5); const bf16x8 x5 = lds_rd128<0>(a5), y5 = lds_rd128<8192>(a5);
;   asm volatile("s_waitcnt lgkmcnt(4)" ::: "memory"); SBAR_M();
;   p0 = __builtin_amdgcn_mfma_f32_32x32x16_bf16(x3, qr[3], p0, 0, 0, 0); p1 = __builtin_amdgcn_mfma_f32_32x32x16_bf16(y3, qr[3], p1, 0, 0, 0);
;   const int a6 = kb ^ (6 << 5); const bf16x8 x6 = lds_rd128<0>(a6), y6 = lds_rd128<8192>(a6);
;   asm volatile("s_waitcnt lgkmcnt(4)" ::: "memory"); SBAR_M();
;   p0 = __builtin_amdgcn_mfma_f32_32x32x16_bf16(x4, qr[4], p0, 0, 0, 0); p1 = __builtin_amdgcn_mfma_f32_32x32x16_bf16(y4, qr[4], p1, 0, 0, 0);
;   const int a7 = kb ^ (7 << 5); const bf16x8 x7 = lds_rd128<0>(a7), y7 = lds_rd128<8192>(a7);
;   asm volatile("s_waitcnt lgkmcnt(4)" ::: "memory"); SBAR_M();
;   p0 = __builtin_amdgcn_mfma_f32_32x32x16_bf16(x5, qr[5], p0, 0, 0, 0); p1 = __builtin_amdgcn_mfma_f32_32x32x16_bf16(y5, qr[5], p1, 0, 0, 0);
;   asm volatile("s_waitcnt lgkmcnt(2)" ::: "memory"); SBAR_M();
;   p0 = __builtin_amdgcn_mfma_f32_32x32x16_bf16(x6, qr[6], p0, 0, 0, 0); p1 = __builtin_amdgcn_mfma_f32_32x32x16_bf16(y6, qr[6], p1, 0, 0, 0);
.LBB0_447:
	v_cmp_neq_f32_e64 s[6:7], v231, -v228
	s_cmp_eq_u64 s[6:7], 0
	s_cselect_b64 s[6:7], -1, 0
	v_cndmask_b32_e64 v97, -v228, v97, s[6:7]
	v_cndmask_b32_e64 v96, -v228, v96, s[6:7]
	v_cndmask_b32_e64 v95, -v228, v95, s[6:7]
	v_cndmask_b32_e64 v94, -v228, v94, s[6:7]
	v_cndmask_b32_e64 v93, -v228, v93, s[6:7]
	v_cndmask_b32_e64 v92, -v228, v92, s[6:7]
	v_cndmask_b32_e64 v91, -v228, v91, s[6:7]
	v_cndmask_b32_e64 v90, -v228, v90, s[6:7]
	v_cndmask_b32_e64 v89, -v228, v89, s[6:7]
	v_cndmask_b32_e64 v88, -v228, v88, s[6:7]
	v_cndmask_b32_e64 v87, -v228, v87, s[6:7]
	v_cndmask_b32_e64 v86, -v228, v86, s[6:7]
	v_cndmask_b32_e64 v85, -v228, v85, s[6:7]
	v_cndmask_b32_e64 v84, -v228, v84, s[6:7]
	v_cndmask_b32_e64 v83, -v228, v83, s[6:7]
	v_cndmask_b32_e64 v82, -v228, v82, s[6:7]
	ds_read_b128 v[98:101], v224 offset:0
	ds_read_b128 v[232:235], v224 offset:0x2000
	ds_read_b128 v[236:239], v223 offset:0
	ds_read_b128 v[240:243], v223 offset:0x2000
	ds_read_b128 v[244:247], v222 offset:0
	ds_read_b128 v[248:251], v222 offset:0x2000
	s_waitcnt lgkmcnt(4)
	s_nop 1
	v_mfma_f32_32x32x16_bf16 v[114:129], v[98:101], v[158:161], v[82:97]
	v_mfma_f32_32x32x16_bf16 v[98:113], v[232:235], v[158:161], v[82:97]
	ds_read_b128 v[232:235], v221 offset:0
	ds_read_b128 v[190:193], v221 offset:0x2000
	s_waitcnt lgkmcnt(4)
	v_mfma_f32_32x32x16_bf16 v[114:129], v[236:239], v[154:157], v[114:129]
	ds_read_b128 v[236:239], v220 offset:0
	v_mfma_f32_32x32x16_bf16 v[98:113], v[240:243], v[154:157], v[98:113]
	ds_read_b128 v[240:243], v220 offset:0x2000
	s_waitcnt lgkmcnt(4)
	v_mfma_f32_32x32x16_bf16 v[114:129], v[244:247], v[150:153], v[114:129]
	ds_read_b128 v[244:247], v219 offset:0
	v_mfma_f32_32x32x16_bf16 v[98:113], v[248:251], v[150:153], v[98:113]
	ds_read_b128 v[248:251], v219 offset:0x2000
	s_waitcnt lgkmcnt(4)
	v_mfma_f32_32x32x16_bf16 v[114:129], v[232:235], v[146:149], v[114:129]
	v_mfma_f32_32x32x16_bf16 v[98:113], v[190:193], v[146:149], v[98:113]
	ds_read_b128 v[190:193], v218 offset:0
	ds_read_b128 v[232:235], v218 offset:0x2000
	s_waitcnt lgkmcnt(4)
	v_mfma_f32_32x32x16_bf16 v[114:129], v[236:239], v[142:145], v[114:129]
	ds_read_b128 v[236:239], v217 offset:0
	v_mfma_f32_32x32x16_bf16 v[98:113], v[240:243], v[142:145], v[98:113]
	ds_read_b128 v[240:243], v217 offset:0x2000
	s_waitcnt lgkmcnt(4)
	v_mfma_f32_32x32x16_bf16 v[114:129], v[244:247], v[138:141], v[114:129]
	s_waitcnt lgkmcnt(2)
	v_mfma_f32_32x32x16_bf16 v[98:113], v[248:251], v[138:141], v[98:113]
	v_mfma_f32_32x32x16_bf16 v[114:129], v[190:193], v[134:137], v[114:129]
	s_waitcnt lgkmcnt(0)
	v_mfma_f32_32x32x16_bf16 v[98:113], v[232:235], v[134:137], v[98:113]
	v_exp_f32_e32 v66, v66
	v_exp_f32_e32 v67, v67
	v_exp_f32_e32 v68, v68
	v_exp_f32_e32 v69, v69
	v_exp_f32_e32 v70, v70
	v_exp_f32_e32 v71, v71
	v_exp_f32_e32 v72, v72
	v_exp_f32_e32 v73, v73
	v_add_f32_e32 v162, v164, v176
	v_add_f32_e32 v189, v175, v188
	v_add_f32_e32 v190, v165, v163
	v_add_f32_e32 v191, v174, v177
	v_exp_f32_e32 v74, v74
	v_exp_f32_e32 v75, v75
	v_exp_f32_e32 v76, v76
	v_exp_f32_e32 v77, v77
	v_add_f32_e32 v162, v166, v162
	v_add_f32_e32 v189, v173, v189
	v_add_f32_e32 v190, v167, v190
	v_add_f32_e32 v191, v172, v191
	v_exp_f32_e32 v78, v78
	v_exp_f32_e32 v79, v79
	v_exp_f32_e32 v80, v80
	v_exp_f32_e32 v81, v81
	v_add_f32_e32 v162, v168, v162
	v_add_f32_e32 v189, v171, v189
	v_add_f32_e32 v190, v169, v190
	v_add_f32_e32 v191, v170, v191
	v_mfma_f32_32x32x16_bf16 v[114:129], v[236:239], v[130:133], v[114:129]
	v_add_f32_e32 v162, v66, v162
	v_add_f32_e32 v189, v67, v189
	v_add_f32_e32 v190, v68, v190
	v_add_f32_e32 v191, v69, v191
	v_add_f32_e32 v162, v70, v162
	v_add_f32_e32 v189, v71, v189
	v_add_f32_e32 v190, v72, v190
	v_mfma_f32_32x32x16_bf16 v[98:113], v[240:243], v[130:133], v[98:113]
	v_add_f32_e32 v191, v73, v191
	v_add_f32_e32 v162, v74, v162
	v_add_f32_e32 v189, v75, v189
	v_add_f32_e32 v190, v76, v190
	v_add_f32_e32 v191, v77, v191
	v_add_f32_e32 v162, v78, v162
	v_add_f32_e32 v189, v79, v189
	v_add_f32_e32 v190, v80, v190
	v_add_f32_e32 v191, v81, v191
	v_add_f32_e32 v162, v162, v189
	v_add_f32_e32 v189, v190, v191
	v_add_f32_e32 v226, v162, v189
	v_mov_b32_e32 v227, v226
	v_cvt_pk_bf16_f32 v162, v176, v188
	v_cvt_pk_bf16_f32 v163, v163, v177
	v_cvt_pk_bf16_f32 v164, v164, v175
	s_nop 1
	v_permlane32_swap_b32_e32 v226, v227
	v_cvt_pk_bf16_f32 v165, v165, v174
	v_cvt_pk_bf16_f32 v166, v166, v173
	v_cvt_pk_bf16_f32 v167, v167, v172
	v_cvt_pk_bf16_f32 v168, v168, v171
	v_cvt_pk_bf16_f32 v169, v169, v170
	v_cvt_pk_bf16_f32 v170, v66, v67
	v_cvt_pk_bf16_f32 v171, v68, v69
	v_cvt_pk_bf16_f32 v172, v70, v71
	v_cvt_pk_bf16_f32 v173, v72, v73
	v_cvt_pk_bf16_f32 v174, v74, v75
	v_cvt_pk_bf16_f32 v175, v76, v77
	v_cvt_pk_bf16_f32 v176, v78, v79
	v_cvt_pk_bf16_f32 v177, v80, v81
	v_lshl_add_u64 v[188:189], v[186:187], 0, v[0:1]
	v_add_co_u32_e32 v66, vcc, s78, v188
	v_lshl_add_u64 v[190:191], v[184:185], 0, v[0:1]
	s_nop 0
	v_addc_co_u32_e32 v67, vcc, 0, v189, vcc
	v_add_co_u32_e32 v70, vcc, s79, v188
	s_nop 1
	v_addc_co_u32_e32 v71, vcc, 0, v189, vcc
	v_add_co_u32_e32 v74, vcc, s70, v190
	global_load_dwordx4 v[66:69], v[66:67], off offset:2176
	s_nop 0
	global_load_dwordx4 v[70:73], v[70:71], off offset:2176
	v_addc_co_u32_e32 v75, vcc, 0, v191, vcc
	v_add_co_u32_e32 v78, vcc, s71, v190
	s_nop 1
	v_addc_co_u32_e32 v79, vcc, 0, v191, vcc
	global_load_dwordx4 v[74:77], v[74:75], off
	s_nop 0
	global_load_dwordx4 v[78:81], v[78:79], off
	ds_read_b64_tr_b16 v[232:233], v199 offset:0
	ds_read_b64_tr_b16 v[234:235], v199 offset:0x800
	ds_read_b64_tr_b16 v[236:237], v199 offset:0x1000
	ds_read_b64_tr_b16 v[238:239], v199 offset:0x1800
	ds_read_b64_tr_b16 v[240:241], v199 offset:0x2000
	ds_read_b64_tr_b16 v[242:243], v199 offset:0x2800
	ds_read_b64_tr_b16 v[244:245], v199 offset:0x3000
	ds_read_b64_tr_b16 v[246:247], v199 offset:0x3800
	ds_read_b64_tr_b16 v[248:249], v199 offset:0x200
	ds_read_b64_tr_b16 v[250:251], v199 offset:0xa00
	s_waitcnt lgkmcnt(8)
; __device__ __forceinline__ void pv_d0(f32x16* o, int vb, bf16x8 pa0, bf16x8 pa1, bf16x8 pa2, bf16x8 pa3) {
;     ...
;   const s16x4 l0 = tr_read<v_rd_off(0, 0, 0)>(vb), h0 = tr_read<v_rd_off(0, 0, 1)>(vb);
;   const s16x4 l1 = tr_read<v_rd_off(0, 1, 0)>(vb), h1 = tr_read<v_rd_off(0, 1, 1)>(vb);
;   const s16x4 l2 = tr_read<v_rd_off(0, 2, 0)>(vb), h2 = tr_read<v_rd_off(0, 2, 1)>(vb);
;   const s16x4 l3 = tr_read<v_rd_off(0, 3, 0)>(vb), h3 = tr_read<v_rd_off(0, 3, 1)>(vb);
;   const s16x4 l4 = tr_read<v_rd_off(1, 0, 0)>(vb), h4 = tr_read<v_rd_off(1, 0, 1)>(vb);
;   asm volatile("s_waitcnt lgkmcnt(8)" ::: "memory"); SBAR();
;   o[0] = __builtin_amdgcn_mfma_f32_32x32x16_bf16(pa0, PK(l0, h0), o[0], 0, 0, 0);
;   const s16x4 l5 = tr_read<v_rd_off(1, 1, 0)>(vb), h5 = tr_read<v_rd_off(1, 1, 1)>(vb);
;   asm volatile("s_waitcnt lgkmcnt(8)" ::: "memory"); SBAR();
;   o[0] = __builtin_amdgcn_mfma_f32_32x32x16_bf16(pa1, PK(l1, h1), o[0], 0, 0, 0);
;   const s16x4 l6 = tr_read<v_rd_off(1, 2, 0)>(vb), h6 = tr_read<v_rd_off(1, 2, 1)>(vb);
;   asm volatile("s_waitcnt lgkmcnt(8)" ::: "memory"); SBAR();
;   o[0] = __builtin_amdgcn_mfma_f32_32x32x16_bf16(pa2, PK(l2, h2), o[0], 0, 0, 0);
;   const s16x4 l7 = tr_read<v_rd_off(1, 3, 0)>(vb), h7 = tr_read<v_rd_off(1, 3, 1)>(vb);
;   asm volatile("s_waitcnt lgkmcnt(8)" ::: "memory"); SBAR();
;   o[0] = __builtin_amdgcn_mfma_f32_32x32x16_bf16(pa3, PK(l3, h3), o[0], 0, 0, 0);
;   const s16x4 l8 = tr_read<v_rd_off(2, 0, 0)>(vb), h8 = tr_read<v_rd_off(2, 0, 1)>(vb);
;   asm volatile("s_waitcnt lgkmcnt(8)" ::: "memory"); SBAR();
;   o[1] = __builtin_amdgcn_mfma_f32_32x32x16_bf16(pa0, PK(l4, h4), o[1], 0, 0, 0);
;   const s16x4 l9 = tr_read<v_rd_off(2, 1, 0)>(vb), h9 = tr_read<v_rd_off(2, 1, 1)>(vb);
;   asm volatile("s_waitcnt lgkmcnt(8)" ::: "memory"); SBAR();
;   o[1] = __builtin_amdgcn_mfma_f32_32x32x16_bf16(pa1, PK(l5, h5), o[1], 0, 0, 0);
;   const s16x4 l10 = tr_read<v_rd_off(2, 2, 0)>(vb), h10 = tr_read<v_rd_off(2, 2, 1)>(vb);
;   asm volatile("s_waitcnt lgkmcnt(8)" ::: "memory"); SBAR();
;   o[1] = __builtin_amdgcn_mfma_f32_32x32x16_bf16(pa2, PK(l6, h6), o[1], 0, 0, 0);
;   const s16x4 l11 = tr_read<v_rd_off(2, 3, 0)>(vb), h11 = tr_read<v_rd_off(2, 3, 1)>(vb);
;   asm volatile("s_waitcnt lgkmcnt(8)" ::: "memory"); SBAR();
;   o[1] = __builtin_amdgcn_mfma_f32_32x32x16_bf16(pa3, PK(l7, h7), o[1], 0, 0, 0);
	s_nop 0
	v_mfma_f32_32x32x16_bf16 v[2:17], v[162:165], v[232:235], v[2:17]
	ds_read_b64_tr_b16 v[232:233], v199 offset:0x1200
	ds_read_b64_tr_b16 v[234:235], v199 offset:0x1a00
	s_waitcnt lgkmcnt(8)
	v_mfma_f32_32x32x16_bf16 v[2:17], v[166:169], v[236:239], v[2:17]
	ds_read_b64_tr_b16 v[236:237], v199 offset:0x2200
	ds_read_b64_tr_b16 v[238:239], v199 offset:0x2a00
	s_waitcnt lgkmcnt(8)
	v_mfma_f32_32x32x16_bf16 v[2:17], v[170:173], v[240:243], v[2:17]
	ds_read_b64_tr_b16 v[240:241], v199 offset:0x3200
	ds_read_b64_tr_b16 v[242:243], v199 offset:0x3a00
	s_waitcnt lgkmcnt(8)
	v_mfma_f32_32x32x16_bf16 v[2:17], v[174:177], v[244:247], v[2:17]
	ds_read_b64_tr_b16 v[244:245], v199 offset:0x400
	ds_read_b64_tr_b16 v[246:247], v199 offset:0xc00
	s_waitcnt lgkmcnt(8)
	v_mfma_f32_32x32x16_bf16 v[50:65], v[162:165], v[248:251], v[50:65]
	ds_read_b64_tr_b16 v[248:249], v199 offset:0x1400
	ds_read_b64_tr_b16 v[250:251], v199 offset:0x1c00
	s_waitcnt lgkmcnt(8)
	v_mfma_f32_32x32x16_bf16 v[50:65], v[166:169], v[232:235], v[50:65]
	ds_read_b64_tr_b16 v[232:233], v199 offset:0x2400
	ds_read_b64_tr_b16 v[234:235], v199 offset:0x2c00
	s_waitcnt lgkmcnt(8)
	v_mfma_f32_32x32x16_bf16 v[50:65], v[170:173], v[236:239], v[50:65]
	ds_read_b64_tr_b16 v[236:237], v199 offset:0x3400
	ds_read_b64_tr_b16 v[238:239], v199 offset:0x3c00
	s_waitcnt lgkmcnt(8)
	v_mfma_f32_32x32x16_bf16 v[50:65], v[174:177], v[240:243], v[50:65]
	ds_read_b64_tr_b16 v[240:241], v199 offset:0x600
	ds_read_b64_tr_b16 v[242:243], v199 offset:0xe00
	s_waitcnt lgkmcnt(8)
	v_mfma_f32_32x32x16_bf16 v[34:49], v[162:165], v[244:247], v[34:49]
	ds_read_b64_tr_b16 v[244:245], v199 offset:0x1600
	ds_read_b64_tr_b16 v[246:247], v199 offset:0x1e00
	s_waitcnt lgkmcnt(8)
	v_mfma_f32_32x32x16_bf16 v[34:49], v[166:169], v[248:251], v[34:49]
	ds_read_b64_tr_b16 v[248:249], v199 offset:0x2600
	ds_read_b64_tr_b16 v[250:251], v199 offset:0x2e00
	s_waitcnt lgkmcnt(8)
	v_mfma_f32_32x32x16_bf16 v[34:49], v[170:173], v[232:235], v[34:49]
	ds_read_b64_tr_b16 v[232:233], v199 offset:0x3600
	ds_read_b64_tr_b16 v[234:235], v199 offset:0x3e00
	s_waitcnt lgkmcnt(8)
	v_mfma_f32_32x32x16_bf16 v[34:49], v[174:177], v[236:239], v[34:49]
	s_waitcnt lgkmcnt(6)
	v_mfma_f32_32x32x16_bf16 v[18:33], v[162:165], v[240:243], v[18:33]
	s_waitcnt lgkmcnt(4)
	v_mfma_f32_32x32x16_bf16 v[18:33], v[166:169], v[244:247], v[18:33]
	s_waitcnt lgkmcnt(2)
	v_mfma_f32_32x32x16_bf16 v[18:33], v[170:173], v[248:251], v[18:33]
	s_waitcnt lgkmcnt(0)
	v_max_f32_e32 v162, v114, v118
	v_max_f32_e32 v163, v115, v119
	v_max_f32_e32 v164, v117, v121
	v_max3_f32 v165, v116, v120, v124
	v_max3_f32 v164, v164, v125, v129
	v_max3_f32 v162, v162, v122, v126
	v_max3_f32 v163, v163, v123, v127
	v_max3_f32 v165, v165, v128, v100
	v_max3_f32 v164, v164, v101, v105
	v_max3_f32 v162, v162, v98, v102
	v_max3_f32 v163, v163, v99, v103
	v_max3_f32 v165, v165, v104, v108
	v_max3_f32 v164, v164, v109, v113
	v_mfma_f32_32x32x16_bf16 v[18:33], v[174:177], v[232:235], v[18:33]
	v_max3_f32 v162, v162, v106, v110
	v_max3_f32 v163, v163, v107, v111
	v_max3_f32 v164, v165, v112, v164
	v_max3_f32 v162, v162, v163, v164
	v_cmp_ge_f32_e32 vcc, s48, v162
	s_cmp_eq_u64 vcc, exec
	s_cbranch_scc0 .LBB0_461
	v_mov_b32_e32 v230, v228
	v_mov_b32_e32 v229, 1.0

; __device__ __forceinline__ void qkt8_roll(f32x16& p0, f32x16& p1, const f32x16& negm, int kb, const bf16x8* qr) {
;   const int a0 = kb ^ (0 << 5); const bf16x8 x0 = lds_rd128<0>(a0), y0 = lds_rd128<8192>(a0);
;   const int a1 = kb ^ (1 << 5); const bf16x8 x1 = lds_rd128<0>(a1), y1 = lds_rd128<8192>(a1);
;   const int a2 = kb ^ (2 << 5); const bf16x8 x2 = lds_rd128<0>(a2), y2 = lds_rd128<8192>(a2);
;   asm volatile("s_waitcnt lgkmcnt(4)" ::: "memory"); SBAR_M();
;   p0 = __builtin_amdgcn_mfma_f32_32x32x16_bf16(x0, qr[0], negm, 0, 0, 0); p1 = __builtin_amdgcn_mfma_f32_32x32x16_bf16(y0, qr[0], negm, 0, 0, 0);
;   const int a3 = kb ^ (3 << 5); const bf16x8 x3 = lds_rd128<0>(a3), y3 = lds_rd128<8192>(a3);
;   asm volatile("s_waitcnt lgkmcnt(4)" ::: "memory"); SBAR_M();
;   p0 = __builtin_amdgcn_mfma_f32_32x32x16_bf16(x1, qr[1], p0, 0, 0, 0); p1 = __builtin_amdgcn_mfma_f32_32x32x16_bf16(y1, qr[1], p1, 0, 0, 0);
;   const int a4 = kb ^ (4 << 5); const bf16x8 x4 = lds_rd128<0>(a4), y4 = lds_rd128<8192>(a4);
;   asm volatile("s_waitcnt lgkmcnt(4)" ::: "memory"); SBAR_M();
;   p0 = __builtin_amdgcn_mfma_f32_32x32x16_bf16(x2, qr[2], p0, 0, 0, 0); p1 = __builtin_amdgcn_mfma_f32_32x32x16_bf16(y2, qr[2], p1, 0, 0, 0);
;   const int a5 = kb ^ (5 << 5); const bf16x8 x5 = lds_rd128<0>(a5), y5 = lds_rd128<8192>(a5);
;   asm volatile("s_waitcnt lgkmcnt(4)" ::: "memory"); SBAR_M();
;   p0 = __builtin_amdgcn_mfma_f32_32x32x16_bf16(x3, qr[3], p0, 0, 0, 0); p1 = __builtin_amdgcn_mfma_f32_32x32x16_bf16(y3, qr[3], p1, 0, 0, 0);
;   const int a6 = kb ^ (6 << 5); const bf16x8 x6 = lds_rd128<0>(a6), y6 = lds_rd128<8192>(a6);
;   asm volatile("s_waitcnt lgkmcnt(4)" ::: "memory"); SBAR_M();
;   p0 = __builtin_amdgcn_mfma_f32_32x32x16_bf16(x4, qr[4], p0, 0, 0, 0); p1 = __builtin_amdgcn_mfma_f32_32x32x16_bf16(y4, qr[4], p1, 0, 0, 0);
;   const int a7 = kb ^ (7 << 5); const bf16x8 x7 = lds_rd128<0>(a7), y7 = lds_rd128<8192>(a7);
;   asm volatile("s_waitcnt lgkmcnt(4)" ::: "memory"); SBAR_M();
;   p0 = __builtin_amdgcn_mfma_f32_32x32x16_bf16(x5, qr[5], p0, 0, 0, 0); p1 = __builtin_amdgcn_mfma_f32_32x32x16_bf16(y5, qr[5], p1, 0, 0, 0);
;   asm volatile("s_waitcnt lgkmcnt(2)" ::: "memory"); SBAR_M();
;   p0 = __builtin_amdgcn_mfma_f32_32x32x16_bf16(x6, qr[6], p0, 0, 0, 0); p1 = __builtin_amdgcn_mfma_f32_32x32x16_bf16(y6, qr[6], p1, 0, 0, 0);
.LBB0_453:
	v_xor_b32_e32 v66, 0x80000000, v228
	v_cndmask_b32_e64 v231, v66, v231, s[6:7]
	v_exp_f32_e32 v162, v114
	v_exp_f32_e32 v163, v116
	v_cmp_neq_f32_e64 s[6:7], v231, -v230
	s_cmp_eq_u64 s[6:7], 0
	s_cselect_b64 s[6:7], -1, 0
	v_cndmask_b32_e64 v97, -v230, v97, s[6:7]
	v_cndmask_b32_e64 v96, -v230, v96, s[6:7]
	v_cndmask_b32_e64 v95, -v230, v95, s[6:7]
	v_cndmask_b32_e64 v94, -v230, v94, s[6:7]
	v_cndmask_b32_e64 v93, -v230, v93, s[6:7]
	v_cndmask_b32_e64 v92, -v230, v92, s[6:7]
	v_cndmask_b32_e64 v91, -v230, v91, s[6:7]
	v_cndmask_b32_e64 v90, -v230, v90, s[6:7]
	v_cndmask_b32_e64 v89, -v230, v89, s[6:7]
	v_cndmask_b32_e64 v88, -v230, v88, s[6:7]
	v_cndmask_b32_e64 v87, -v230, v87, s[6:7]
	v_cndmask_b32_e64 v86, -v230, v86, s[6:7]
	v_cndmask_b32_e64 v85, -v230, v85, s[6:7]
	v_cndmask_b32_e64 v84, -v230, v84, s[6:7]
	v_cndmask_b32_e64 v83, -v230, v83, s[6:7]
	v_cndmask_b32_e64 v82, -v230, v82, s[6:7]
	v_exp_f32_e32 v177, v115
	v_exp_f32_e32 v176, v117
	v_exp_f32_e32 v164, v118
	v_exp_f32_e32 v175, v119
	v_exp_f32_e32 v165, v120
	v_exp_f32_e32 v174, v121
	v_exp_f32_e32 v166, v122
	v_exp_f32_e32 v173, v123
	v_exp_f32_e32 v167, v124
	v_exp_f32_e32 v172, v125
	v_exp_f32_e32 v168, v126
	v_exp_f32_e32 v171, v127
	v_exp_f32_e32 v169, v128
	v_exp_f32_e32 v170, v129
	s_waitcnt lgkmcnt(0)
	s_barrier
	ds_read_b128 v[66:69], v200 offset:0
	ds_read_b128 v[232:235], v200 offset:0x2000
	ds_read_b128 v[236:239], v210 offset:0
	ds_read_b128 v[240:243], v210 offset:0x2000
	ds_read_b128 v[244:247], v211 offset:0
	ds_read_b128 v[248:251], v211 offset:0x2000
	s_waitcnt lgkmcnt(4)
	s_nop 0
	v_mfma_f32_32x32x16_bf16 v[114:129], v[66:69], v[158:161], v[82:97]
	v_mfma_f32_32x32x16_bf16 v[66:81], v[232:235], v[158:161], v[82:97]
	ds_read_b128 v[232:235], v212 offset:0
	ds_read_b128 v[192:195], v212 offset:0x2000
	s_waitcnt lgkmcnt(4)
	v_mfma_f32_32x32x16_bf16 v[114:129], v[236:239], v[154:157], v[114:129]
	ds_read_b128 v[236:239], v213 offset:0
	v_mfma_f32_32x32x16_bf16 v[66:81], v[240:243], v[154:157], v[66:81]
	ds_read_b128 v[240:243], v213 offset:0x2000
	s_waitcnt lgkmcnt(4)
	v_mfma_f32_32x32x16_bf16 v[114:129], v[244:247], v[150:153], v[114:129]
	ds_read_b128 v[244:247], v214 offset:0
	v_mfma_f32_32x32x16_bf16 v[66:81], v[248:251], v[150:153], v[66:81]
	ds_read_b128 v[248:251], v214 offset:0x2000
	s_waitcnt lgkmcnt(4)
	v_mfma_f32_32x32x16_bf16 v[114:129], v[232:235], v[146:149], v[114:129]
	v_mfma_f32_32x32x16_bf16 v[66:81], v[192:195], v[146:149], v[66:81]
	ds_read_b128 v[192:195], v215 offset:0
	ds_read_b128 v[232:235], v215 offset:0x2000
	s_waitcnt lgkmcnt(4)
	v_mfma_f32_32x32x16_bf16 v[114:129], v[236:239], v[142:145], v[114:129]
	ds_read_b128 v[236:239], v216 offset:0
	v_mfma_f32_32x32x16_bf16 v[66:81], v[240:243], v[142:145], v[66:81]
	ds_read_b128 v[240:243], v216 offset:0x2000
	s_waitcnt lgkmcnt(4)
	v_mfma_f32_32x32x16_bf16 v[114:129], v[244:247], v[138:141], v[114:129]
	s_waitcnt lgkmcnt(2)
	v_mfma_f32_32x32x16_bf16 v[66:81], v[248:251], v[138:141], v[66:81]
	v_mfma_f32_32x32x16_bf16 v[114:129], v[192:195], v[134:137], v[114:129]
	s_waitcnt lgkmcnt(0)
	v_mfma_f32_32x32x16_bf16 v[66:81], v[232:235], v[134:137], v[66:81]
	v_exp_f32_e32 v98, v98
	v_exp_f32_e32 v99, v99
	v_exp_f32_e32 v100, v100
	v_exp_f32_e32 v101, v101
	v_exp_f32_e32 v102, v102
	v_exp_f32_e32 v103, v103
	v_exp_f32_e32 v104, v104
	v_exp_f32_e32 v105, v105
	v_add_f32_e32 v192, v164, v162
	v_add_f32_e32 v193, v175, v177
	v_add_f32_e32 v194, v165, v163
	v_add_f32_e32 v195, v174, v176
	v_exp_f32_e32 v106, v106
	v_exp_f32_e32 v107, v107
	v_exp_f32_e32 v108, v108
	v_exp_f32_e32 v109, v109
	v_add_f32_e32 v192, v166, v192
	v_add_f32_e32 v193, v173, v193
	v_add_f32_e32 v194, v167, v194
	v_add_f32_e32 v195, v172, v195
	v_exp_f32_e32 v110, v110
	v_exp_f32_e32 v111, v111
	v_exp_f32_e32 v112, v112
	v_exp_f32_e32 v113, v113
	v_add_f32_e32 v192, v168, v192
	v_add_f32_e32 v193, v171, v193
	v_add_f32_e32 v194, v169, v194
	v_add_f32_e32 v195, v170, v195
	v_mfma_f32_32x32x16_bf16 v[114:129], v[236:239], v[130:133], v[114:129]
	v_add_f32_e32 v192, v98, v192
	v_add_f32_e32 v193, v193, v99
	v_add_f32_e32 v194, v194, v100
	v_add_f32_e32 v195, v195, v101
	v_add_f32_e32 v192, v102, v192
	v_add_f32_e32 v193, v103, v193
	v_add_f32_e32 v194, v104, v194
	v_mfma_f32_32x32x16_bf16 v[66:81], v[240:243], v[130:133], v[66:81]
	v_add_f32_e32 v195, v105, v195
	v_add_f32_e32 v192, v106, v192
	v_add_f32_e32 v193, v107, v193
	v_add_f32_e32 v194, v108, v194
	v_add_f32_e32 v195, v109, v195
	v_add_f32_e32 v192, v110, v192
	v_add_f32_e32 v193, v111, v193
	v_add_f32_e32 v194, v112, v194
	v_add_f32_e32 v195, v113, v195
	v_add_f32_e32 v192, v192, v193
	v_add_f32_e32 v193, v194, v195
	v_add_f32_e32 v232, v192, v193
	v_mov_b32_e32 v233, v232
	v_cvt_pk_bf16_f32 v162, v162, v177
	v_cvt_pk_bf16_f32 v163, v163, v176
	v_cvt_pk_bf16_f32 v164, v164, v175
	v_cvt_pk_bf16_f32 v165, v165, v174
	s_nop 1
	v_permlane32_swap_b32_e32 v232, v233
	v_cvt_pk_bf16_f32 v166, v166, v173
	v_cvt_pk_bf16_f32 v167, v167, v172
	v_cvt_pk_bf16_f32 v168, v168, v171
	v_cvt_pk_bf16_f32 v169, v169, v170
	v_cvt_pk_bf16_f32 v170, v98, v99
	v_cvt_pk_bf16_f32 v171, v100, v101
	v_cvt_pk_bf16_f32 v172, v102, v103
	v_cvt_pk_bf16_f32 v173, v104, v105
	v_cvt_pk_bf16_f32 v174, v106, v107
	v_cvt_pk_bf16_f32 v175, v108, v109
	v_cvt_pk_bf16_f32 v176, v110, v111
	v_cvt_pk_bf16_f32 v177, v112, v113
	s_nop 0
	v_add_co_u32_e32 v98, vcc, s72, v188
	s_nop 1
	v_addc_co_u32_e32 v99, vcc, 0, v189, vcc
	v_add_co_u32_e32 v102, vcc, s73, v188
	s_nop 1
	v_addc_co_u32_e32 v103, vcc, 0, v189, vcc
	v_add_co_u32_e32 v106, vcc, s33, v190
	global_load_dwordx4 v[98:101], v[98:99], off offset:2176
	s_nop 0
	global_load_dwordx4 v[102:105], v[102:103], off offset:2176
	v_addc_co_u32_e32 v107, vcc, 0, v191, vcc
	v_add_co_u32_e32 v110, vcc, s52, v190
	s_nop 1
	v_addc_co_u32_e32 v111, vcc, 0, v191, vcc
	global_load_dwordx4 v[106:109], v[106:107], off
	s_nop 0
	global_load_dwordx4 v[110:113], v[110:111], off
	ds_read_b64_tr_b16 v[188:189], v198 offset:0
	ds_read_b64_tr_b16 v[190:191], v198 offset:0x800
	ds_read_b64_tr_b16 v[192:193], v198 offset:0x1000
	ds_read_b64_tr_b16 v[194:195], v198 offset:0x1800
	ds_read_b64_tr_b16 v[234:235], v198 offset:0x2000
	ds_read_b64_tr_b16 v[236:237], v198 offset:0x2800
	ds_read_b64_tr_b16 v[238:239], v198 offset:0x3000
	ds_read_b64_tr_b16 v[240:241], v198 offset:0x3800
	ds_read_b64_tr_b16 v[242:243], v198 offset:0x200
	ds_read_b64_tr_b16 v[244:245], v198 offset:0xa00
	s_waitcnt lgkmcnt(8)
; __device__ __forceinline__ void pv_d0(f32x16* o, int vb, bf16x8 pa0, bf16x8 pa1, bf16x8 pa2, bf16x8 pa3) {
;     ...
;   const s16x4 l0 = tr_read<v_rd_off(0, 0, 0)>(vb), h0 = tr_read<v_rd_off(0, 0, 1)>(vb);
;   const s16x4 l1 = tr_read<v_rd_off(0, 1, 0)>(vb), h1 = tr_read<v_rd_off(0, 1, 1)>(vb);
;   const s16x4 l2 = tr_read<v_rd_off(0, 2, 0)>(vb), h2 = tr_read<v_rd_off(0, 2, 1)>(vb);
;   const s16x4 l3 = tr_read<v_rd_off(0, 3, 0)>(vb), h3 = tr_read<v_rd_off(0, 3, 1)>(vb);
;   const s16x4 l4 = tr_read<v_rd_off(1, 0, 0)>(vb), h4 = tr_read<v_rd_off(1, 0, 1)>(vb);
;   asm volatile("s_waitcnt lgkmcnt(8)" ::: "memory"); SBAR();
;   o[0] = __builtin_amdgcn_mfma_f32_32x32x16_bf16(pa0, PK(l0, h0), o[0], 0, 0, 0);
;   const s16x4 l5 = tr_read<v_rd_off(1, 1, 0)>(vb), h5 = tr_read<v_rd_off(1, 1, 1)>(vb);
;   asm volatile("s_waitcnt lgkmcnt(8)" ::: "memory"); SBAR();
;   o[0] = __builtin_amdgcn_mfma_f32_32x32x16_bf16(pa1, PK(l1, h1), o[0], 0, 0, 0);
;   const s16x4 l6 = tr_read<v_rd_off(1, 2, 0)>(vb), h6 = tr_read<v_rd_off(1, 2, 1)>(vb);
;   asm volatile("s_waitcnt lgkmcnt(8)" ::: "memory"); SBAR();
;   o[0] = __builtin_amdgcn_mfma_f32_32x32x16_bf16(pa2, PK(l2, h2), o[0], 0, 0, 0);
;   const s16x4 l7 = tr_read<v_rd_off(1, 3, 0)>(vb), h7 = tr_read<v_rd_off(1, 3, 1)>(vb);
;   asm volatile("s_waitcnt lgkmcnt(8)" ::: "memory"); SBAR();
;   o[0] = __builtin_amdgcn_mfma_f32_32x32x16_bf16(pa3, PK(l3, h3), o[0], 0, 0, 0);
;   const s16x4 l8 = tr_read<v_rd_off(2, 0, 0)>(vb), h8 = tr_read<v_rd_off(2, 0, 1)>(vb);
;   asm volatile("s_waitcnt lgkmcnt(8)" ::: "memory"); SBAR();
;   o[1] = __builtin_amdgcn_mfma_f32_32x32x16_bf16(pa0, PK(l4, h4), o[1], 0, 0, 0);
;   const s16x4 l9 = tr_read<v_rd_off(2, 1, 0)>(vb), h9 = tr_read<v_rd_off(2, 1, 1)>(vb);
;   asm volatile("s_waitcnt lgkmcnt(8)" ::: "memory"); SBAR();
;   o[1] = __builtin_amdgcn_mfma_f32_32x32x16_bf16(pa1, PK(l5, h5), o[1], 0, 0, 0);
;   const s16x4 l10 = tr_read<v_rd_off(2, 2, 0)>(vb), h10 = tr_read<v_rd_off(2, 2, 1)>(vb);
;   asm volatile("s_waitcnt lgkmcnt(8)" ::: "memory"); SBAR();
;   o[1] = __builtin_amdgcn_mfma_f32_32x32x16_bf16(pa2, PK(l6, h6), o[1], 0, 0, 0);
;   const s16x4 l11 = tr_read<v_rd_off(2, 3, 0)>(vb), h11 = tr_read<v_rd_off(2, 3, 1)>(vb);
;   asm volatile("s_waitcnt lgkmcnt(8)" ::: "memory"); SBAR();
;   o[1] = __builtin_amdgcn_mfma_f32_32x32x16_bf16(pa3, PK(l7, h7), o[1], 0, 0, 0);
	s_nop 0
	v_mfma_f32_32x32x16_bf16 v[2:17], v[162:165], v[188:191], v[2:17]
	ds_read_b64_tr_b16 v[188:189], v198 offset:0x1200
	ds_read_b64_tr_b16 v[190:191], v198 offset:0x1a00
	s_waitcnt lgkmcnt(8)
	v_mfma_f32_32x32x16_bf16 v[2:17], v[166:169], v[192:195], v[2:17]
	ds_read_b64_tr_b16 v[192:193], v198 offset:0x2200
	ds_read_b64_tr_b16 v[194:195], v198 offset:0x2a00
	s_waitcnt lgkmcnt(8)
	v_mfma_f32_32x32x16_bf16 v[2:17], v[170:173], v[234:237], v[2:17]
	ds_read_b64_tr_b16 v[234:235], v198 offset:0x3200
	ds_read_b64_tr_b16 v[236:237], v198 offset:0x3a00
	s_waitcnt lgkmcnt(8)
	v_mfma_f32_32x32x16_bf16 v[2:17], v[174:177], v[238:241], v[2:17]
	ds_read_b64_tr_b16 v[238:239], v198 offset:0x400
	ds_read_b64_tr_b16 v[240:241], v198 offset:0xc00
	s_waitcnt lgkmcnt(8)
	v_mfma_f32_32x32x16_bf16 v[50:65], v[162:165], v[242:245], v[50:65]
	ds_read_b64_tr_b16 v[242:243], v198 offset:0x1400
	ds_read_b64_tr_b16 v[244:245], v198 offset:0x1c00
	s_waitcnt lgkmcnt(8)
	v_mfma_f32_32x32x16_bf16 v[50:65], v[166:169], v[188:191], v[50:65]
	ds_read_b64_tr_b16 v[188:189], v198 offset:0x2400
	ds_read_b64_tr_b16 v[190:191], v198 offset:0x2c00
	s_waitcnt lgkmcnt(8)
	v_mfma_f32_32x32x16_bf16 v[50:65], v[170:173], v[192:195], v[50:65]
	ds_read_b64_tr_b16 v[192:193], v198 offset:0x3400
	ds_read_b64_tr_b16 v[194:195], v198 offset:0x3c00
	s_waitcnt lgkmcnt(8)
	v_mfma_f32_32x32x16_bf16 v[50:65], v[174:177], v[234:237], v[50:65]
	ds_read_b64_tr_b16 v[234:235], v198 offset:0x600
	ds_read_b64_tr_b16 v[236:237], v198 offset:0xe00
	s_waitcnt lgkmcnt(8)
	v_mfma_f32_32x32x16_bf16 v[34:49], v[162:165], v[238:241], v[34:49]
	ds_read_b64_tr_b16 v[238:239], v198 offset:0x1600
	ds_read_b64_tr_b16 v[240:241], v198 offset:0x1e00
	s_waitcnt lgkmcnt(8)
	v_mfma_f32_32x32x16_bf16 v[34:49], v[166:169], v[242:245], v[34:49]
	ds_read_b64_tr_b16 v[242:243], v198 offset:0x2600
	ds_read_b64_tr_b16 v[244:245], v198 offset:0x2e00
	s_waitcnt lgkmcnt(8)
	v_mfma_f32_32x32x16_bf16 v[34:49], v[170:173], v[188:191], v[34:49]
	ds_read_b64_tr_b16 v[188:189], v198 offset:0x3600
	ds_read_b64_tr_b16 v[190:191], v198 offset:0x3e00
	s_waitcnt lgkmcnt(8)
	v_mfma_f32_32x32x16_bf16 v[34:49], v[174:177], v[192:195], v[34:49]
	s_waitcnt lgkmcnt(6)
	v_mfma_f32_32x32x16_bf16 v[18:33], v[162:165], v[234:237], v[18:33]
	s_waitcnt lgkmcnt(4)
	v_mfma_f32_32x32x16_bf16 v[18:33], v[166:169], v[238:241], v[18:33]
	s_waitcnt lgkmcnt(2)
	v_mfma_f32_32x32x16_bf16 v[18:33], v[170:173], v[242:245], v[18:33]
	s_waitcnt lgkmcnt(0)
	v_max_f32_e32 v162, v114, v118
	v_max_f32_e32 v163, v115, v119
	v_max_f32_e32 v164, v117, v121
	v_max3_f32 v165, v116, v120, v124
	v_max3_f32 v164, v164, v125, v129
	v_max3_f32 v162, v162, v122, v126
	v_max3_f32 v163, v163, v123, v127
	v_max3_f32 v165, v165, v128, v68
	v_max3_f32 v164, v164, v69, v73
	v_max3_f32 v162, v162, v66, v70
	v_max3_f32 v163, v163, v67, v71
	v_max3_f32 v165, v165, v72, v76
	v_max3_f32 v164, v164, v77, v81
	v_mfma_f32_32x32x16_bf16 v[18:33], v[174:177], v[188:191], v[18:33]
	v_max3_f32 v162, v162, v74, v78
	v_max3_f32 v163, v163, v75, v79
	v_max3_f32 v164, v165, v80, v164
	v_max3_f32 v162, v162, v163, v164
	v_mov_b32_e32 v163, v162
	v_cmp_ge_f32_e32 vcc, s48, v163
	s_cmp_eq_u64 vcc, exec
	v_mov_b32_e32 v162, 1.0
	s_cbranch_scc0 .LBB0_462
	v_mov_b32_e32 v228, v230

; template <bool FIRST>
; __device__ __forceinline__ void partialSM(f32x16& p0, f32x16& p1, float& mC, float& alpha) {
;     ...
;   { auto rr = __builtin_amdgcn_permlane32_swap(__float_as_uint(pmax), __float_as_uint(pmax), false, false);
;     pmax = fmaxf(__uint_as_float(rr[0]), __uint_as_float(rr[1])); }
;   if (!FIRST && __builtin_expect(__all(pmax <= THR2), 1)) { alpha = 1.f; }
;   else { const float delta = FIRST ? fmaxf(pmax, -200.f) : fmaxf(pmax, 0.f); alpha = FIRST ? 1.f : __builtin_amdgcn_exp2f(-delta); mC += delta;
; #pragma unroll
;     for (int r = 0; r < 16; ++r) p0[r] -= delta;
; #pragma unroll
;     for (int r = 0; r < 16; ++r) p1[r] -= delta; }
.LBB0_461:
	v_mov_b32_e32 v163, v162
	s_nop 1
	v_permlane32_swap_b32_e32 v162, v163
	v_max_f32_e32 v162, v162, v163
	v_max_f32_e32 v162, v162, v162
	v_max_f32_e32 v162, 0, v162
	v_exp_f32_e64 v229, -v162
	v_add_f32_e32 v230, v228, v162
	v_pk_add_f32 v[114:115], v[114:115], v[162:163] op_sel_hi:[1,0] neg_lo:[0,1] neg_hi:[0,1]
	v_pk_add_f32 v[116:117], v[116:117], v[162:163] op_sel_hi:[1,0] neg_lo:[0,1] neg_hi:[0,1]
	v_pk_add_f32 v[118:119], v[118:119], v[162:163] op_sel_hi:[1,0] neg_lo:[0,1] neg_hi:[0,1]
	v_pk_add_f32 v[120:121], v[120:121], v[162:163] op_sel_hi:[1,0] neg_lo:[0,1] neg_hi:[0,1]
	v_pk_add_f32 v[122:123], v[122:123], v[162:163] op_sel_hi:[1,0] neg_lo:[0,1] neg_hi:[0,1]
	v_pk_add_f32 v[124:125], v[124:125], v[162:163] op_sel_hi:[1,0] neg_lo:[0,1] neg_hi:[0,1]
	v_pk_add_f32 v[126:127], v[126:127], v[162:163] op_sel_hi:[1,0] neg_lo:[0,1] neg_hi:[0,1]
	v_pk_add_f32 v[128:129], v[128:129], v[162:163] op_sel_hi:[1,0] neg_lo:[0,1] neg_hi:[0,1]
	v_sub_f32_e32 v113, v113, v162
	v_sub_f32_e32 v112, v112, v162
	v_sub_f32_e32 v111, v111, v162
	v_sub_f32_e32 v110, v110, v162
	v_sub_f32_e32 v109, v109, v162
	v_sub_f32_e32 v108, v108, v162
	v_sub_f32_e32 v107, v107, v162
	v_sub_f32_e32 v106, v106, v162
	v_sub_f32_e32 v105, v105, v162
	v_sub_f32_e32 v104, v104, v162
	v_sub_f32_e32 v103, v103, v162
	v_sub_f32_e32 v102, v102, v162
	v_sub_f32_e32 v101, v101, v162
	v_sub_f32_e32 v100, v100, v162
	v_sub_f32_e32 v99, v99, v162
	v_sub_f32_e32 v98, v98, v162
	s_branch .LBB0_449
.LBB0_462:
	v_mov_b32_e32 v162, v163
	s_nop 1
	v_permlane32_swap_b32_e32 v163, v162
	v_max_f32_e32 v163, v163, v162
	v_max_f32_e32 v162, v163, v163
	v_max_f32_e32 v164, 0, v162
	v_exp_f32_e64 v162, -v164
	v_add_f32_e32 v228, v230, v164
	v_pk_add_f32 v[114:115], v[114:115], v[164:165] op_sel_hi:[1,0] neg_lo:[0,1] neg_hi:[0,1]
	v_pk_add_f32 v[116:117], v[116:117], v[164:165] op_sel_hi:[1,0] neg_lo:[0,1] neg_hi:[0,1]
	v_pk_add_f32 v[118:119], v[118:119], v[164:165] op_sel_hi:[1,0] neg_lo:[0,1] neg_hi:[0,1]
	v_pk_add_f32 v[120:121], v[120:121], v[164:165] op_sel_hi:[1,0] neg_lo:[0,1] neg_hi:[0,1]
	v_pk_add_f32 v[122:123], v[122:123], v[164:165] op_sel_hi:[1,0] neg_lo:[0,1] neg_hi:[0,1]
	v_pk_add_f32 v[124:125], v[124:125], v[164:165] op_sel_hi:[1,0] neg_lo:[0,1] neg_hi:[0,1]
	v_pk_add_f32 v[126:127], v[126:127], v[164:165] op_sel_hi:[1,0] neg_lo:[0,1] neg_hi:[0,1]
	v_pk_add_f32 v[128:129], v[128:129], v[164:165] op_sel_hi:[1,0] neg_lo:[0,1] neg_hi:[0,1]
	v_sub_f32_e32 v81, v81, v164
	v_sub_f32_e32 v80, v80, v164
	v_sub_f32_e32 v79, v79, v164
	v_sub_f32_e32 v78, v78, v164
	v_sub_f32_e32 v77, v77, v164
	v_sub_f32_e32 v76, v76, v164
	v_sub_f32_e32 v75, v75, v164
	v_sub_f32_e32 v74, v74, v164
	v_sub_f32_e32 v73, v73, v164
	v_sub_f32_e32 v72, v72, v164
	v_sub_f32_e32 v71, v71, v164
	v_sub_f32_e32 v70, v70, v164
	v_sub_f32_e32 v69, v69, v164
	v_sub_f32_e32 v68, v68, v164
	v_sub_f32_e32 v67, v67, v164
	v_sub_f32_e32 v66, v66, v164
	s_branch .LBB0_455

; __device__ __forceinline__ void pv_psm(f32x16* o, int vb, bf16x8 pa0, bf16x8 pa1, bf16x8 pa2, bf16x8 pa3, f32x16& n0, f32x16& n1, float& mC, float& alpha) {
;   float mx[4];
;     ...
;   const s16x4 l0 = tr_read<v_rd_off(0, 0, 0)>(vb), h0 = tr_read<v_rd_off(0, 0, 1)>(vb);
;   const s16x4 l1 = tr_read<v_rd_off(0, 1, 0)>(vb), h1 = tr_read<v_rd_off(0, 1, 1)>(vb);
;   const s16x4 l2 = tr_read<v_rd_off(0, 2, 0)>(vb), h2 = tr_read<v_rd_off(0, 2, 1)>(vb);
;   const s16x4 l3 = tr_read<v_rd_off(0, 3, 0)>(vb), h3 = tr_read<v_rd_off(0, 3, 1)>(vb);
;   asm volatile("s_waitcnt lgkmcnt(6)" ::: "memory"); SBAR();
;   o[0] = __builtin_amdgcn_mfma_f32_32x32x16_bf16(pa0, PK(l0, h0), o[0], 0, 0, 0);
;   psm_slice<0>(n0, n1, mC, alpha, mx); SBAR();
;   const s16x4 l4 = tr_read<v_rd_off(1, 0, 0)>(vb), h4 = tr_read<v_rd_off(1, 0, 1)>(vb);
;   asm volatile("s_waitcnt lgkmcnt(6)" ::: "memory"); SBAR();
;   o[0] = __builtin_amdgcn_mfma_f32_32x32x16_bf16(pa1, PK(l1, h1), o[0], 0, 0, 0);
;   psm_slice<1>(n0, n1, mC, alpha, mx); SBAR();
;   const s16x4 l5 = tr_read<v_rd_off(1, 1, 0)>(vb), h5 = tr_read<v_rd_off(1, 1, 1)>(vb);
;   asm volatile("s_waitcnt lgkmcnt(6)" ::: "memory"); SBAR();
;   o[0] = __builtin_amdgcn_mfma_f32_32x32x16_bf16(pa2, PK(l2, h2), o[0], 0, 0, 0);
;   psm_slice<2>(n0, n1, mC, alpha, mx); SBAR();
;   const s16x4 l6 = tr_read<v_rd_off(1, 2, 0)>(vb), h6 = tr_read<v_rd_off(1, 2, 1)>(vb);
;   asm volatile("s_waitcnt lgkmcnt(6)" ::: "memory"); SBAR();
;   o[0] = __builtin_amdgcn_mfma_f32_32x32x16_bf16(pa3, PK(l3, h3), o[0], 0, 0, 0);
;   psm_slice<3>(n0, n1, mC, alpha, mx); SBAR();
;   const s16x4 l7 = tr_read<v_rd_off(1, 3, 0)>(vb), h7 = tr_read<v_rd_off(1, 3, 1)>(vb);
;   asm volatile("s_waitcnt lgkmcnt(6)" ::: "memory"); SBAR();
;   o[1] = __builtin_amdgcn_mfma_f32_32x32x16_bf16(pa0, PK(l4, h4), o[1], 0, 0, 0);
;   psm_slice<4>(n0, n1, mC, alpha, mx); SBAR();
;   const s16x4 l8 = tr_read<v_rd_off(2, 0, 0)>(vb), h8 = tr_read<v_rd_off(2, 0, 1)>(vb);
;   asm volatile("s_waitcnt lgkmcnt(6)" ::: "memory"); SBAR();
;   o[1] = __builtin_amdgcn_mfma_f32_32x32x16_bf16(pa1, PK(l5, h5), o[1], 0, 0, 0);
;   psm_slice<5>(n0, n1, mC, alpha, mx); SBAR();
;   const s16x4 l9 = tr_read<v_rd_off(2, 1, 0)>(vb), h9 = tr_read<v_rd_off(2, 1, 1)>(vb);
;   asm volatile("s_waitcnt lgkmcnt(6)" ::: "memory"); SBAR();
;   o[1] = __builtin_amdgcn_mfma_f32_32x32x16_bf16(pa2, PK(l6, h6), o[1], 0, 0, 0);
.LBB0_488:
	ds_read_b64_tr_b16 v[178:179], v211 offset:0
	ds_read_b64_tr_b16 v[180:181], v211 offset:0x800
	ds_read_b64_tr_b16 v[182:183], v211 offset:0x1000
	ds_read_b64_tr_b16 v[184:185], v211 offset:0x1800
	ds_read_b64_tr_b16 v[186:187], v211 offset:0x2000
	ds_read_b64_tr_b16 v[188:189], v211 offset:0x2800
	ds_read_b64_tr_b16 v[192:193], v211 offset:0x3000
	ds_read_b64_tr_b16 v[194:195], v211 offset:0x3800
	s_waitcnt lgkmcnt(6)
	s_nop 0
	v_mfma_f32_32x32x16_bf16 v[50:65], v[146:149], v[178:181], v[50:65]
	ds_read_b64_tr_b16 v[178:179], v211 offset:0x200
	ds_read_b64_tr_b16 v[180:181], v211 offset:0xa00
	s_waitcnt lgkmcnt(6)
	v_mfma_f32_32x32x16_bf16 v[50:65], v[150:153], v[182:185], v[50:65]
	v_max_f32_e32 v182, v102, v102
	v_max_f32_e32 v202, v98, v182
	v_max_f32_e32 v182, v103, v103
	v_max_f32_e32 v203, v99, v182
	v_max_f32_e32 v182, v105, v105
	v_max_f32_e32 v204, v101, v182
	ds_read_b64_tr_b16 v[182:183], v211 offset:0x1200
	ds_read_b64_tr_b16 v[184:185], v211 offset:0x1a00
	s_waitcnt lgkmcnt(6)
	v_mfma_f32_32x32x16_bf16 v[50:65], v[154:157], v[186:189], v[50:65]
	v_max3_f32 v205, v100, v104, v108
	ds_read_b64_tr_b16 v[186:187], v211 offset:0x2200
	ds_read_b64_tr_b16 v[188:189], v211 offset:0x2a00
	s_waitcnt lgkmcnt(6)
	v_mfma_f32_32x32x16_bf16 v[50:65], v[158:161], v[192:195], v[50:65]
	v_max3_f32 v202, v202, v106, v110
	v_max3_f32 v203, v203, v107, v111
	v_max3_f32 v204, v204, v109, v113
	ds_read_b64_tr_b16 v[192:193], v211 offset:0x3200
	ds_read_b64_tr_b16 v[194:195], v211 offset:0x3a00
	s_waitcnt lgkmcnt(6)
	v_mfma_f32_32x32x16_bf16 v[34:49], v[146:149], v[178:181], v[34:49]
	v_max3_f32 v205, v205, v112, v84
	ds_read_b64_tr_b16 v[244:245], v211 offset:0x400
	ds_read_b64_tr_b16 v[246:247], v211 offset:0xc00
	s_waitcnt lgkmcnt(6)
	v_mfma_f32_32x32x16_bf16 v[34:49], v[150:153], v[182:185], v[34:49]
	v_max3_f32 v202, v202, v82, v86
	v_max3_f32 v203, v203, v83, v87
	v_max3_f32 v204, v204, v85, v89
	ds_read_b64_tr_b16 v[178:179], v211 offset:0x1400
	ds_read_b64_tr_b16 v[180:181], v211 offset:0x1c00
	s_waitcnt lgkmcnt(6)
	v_mfma_f32_32x32x16_bf16 v[34:49], v[154:157], v[186:189], v[34:49]
	v_max3_f32 v205, v205, v88, v92
	ds_read_b64_tr_b16 v[182:183], v211 offset:0x2400
	ds_read_b64_tr_b16 v[184:185], v211 offset:0x2c00
	s_waitcnt lgkmcnt(6)
	v_mfma_f32_32x32x16_bf16 v[34:49], v[158:161], v[192:195], v[34:49]
	v_max3_f32 v192, v202, v90, v94
	v_max3_f32 v193, v203, v91, v95
	v_max3_f32 v194, v204, v93, v97
	ds_read_b64_tr_b16 v[186:187], v211 offset:0x3400
	ds_read_b64_tr_b16 v[188:189], v211 offset:0x3c00
	s_waitcnt lgkmcnt(6)
	v_mfma_f32_32x32x16_bf16 v[18:33], v[146:149], v[244:247], v[18:33]
	v_max3_f32 v194, v205, v96, v194
	v_max3_f32 v192, v192, v193, v194
	v_cmp_ge_f32_e32 vcc, s48, v192
	s_cmp_eq_u64 vcc, exec
	v_mov_b32_e32 v242, 1.0
	s_cbranch_scc0 .LBB0_502

; __device__ __forceinline__ void pv_psm(f32x16* o, int vb, bf16x8 pa0, bf16x8 pa1, bf16x8 pa2, bf16x8 pa3, f32x16& n0, f32x16& n1, float& mC, float& alpha) {
;   float mx[4];
;     ...
;   const s16x4 l0 = tr_read<v_rd_off(0, 0, 0)>(vb), h0 = tr_read<v_rd_off(0, 0, 1)>(vb);
;   const s16x4 l1 = tr_read<v_rd_off(0, 1, 0)>(vb), h1 = tr_read<v_rd_off(0, 1, 1)>(vb);
;   const s16x4 l2 = tr_read<v_rd_off(0, 2, 0)>(vb), h2 = tr_read<v_rd_off(0, 2, 1)>(vb);
;   const s16x4 l3 = tr_read<v_rd_off(0, 3, 0)>(vb), h3 = tr_read<v_rd_off(0, 3, 1)>(vb);
;   asm volatile("s_waitcnt lgkmcnt(6)" ::: "memory"); SBAR();
;   o[0] = __builtin_amdgcn_mfma_f32_32x32x16_bf16(pa0, PK(l0, h0), o[0], 0, 0, 0);
;   psm_slice<0>(n0, n1, mC, alpha, mx); SBAR();
;   const s16x4 l4 = tr_read<v_rd_off(1, 0, 0)>(vb), h4 = tr_read<v_rd_off(1, 0, 1)>(vb);
;   asm volatile("s_waitcnt lgkmcnt(6)" ::: "memory"); SBAR();
;   o[0] = __builtin_amdgcn_mfma_f32_32x32x16_bf16(pa1, PK(l1, h1), o[0], 0, 0, 0);
;   psm_slice<1>(n0, n1, mC, alpha, mx); SBAR();
;   const s16x4 l5 = tr_read<v_rd_off(1, 1, 0)>(vb), h5 = tr_read<v_rd_off(1, 1, 1)>(vb);
;   asm volatile("s_waitcnt lgkmcnt(6)" ::: "memory"); SBAR();
;   o[0] = __builtin_amdgcn_mfma_f32_32x32x16_bf16(pa2, PK(l2, h2), o[0], 0, 0, 0);
;   psm_slice<2>(n0, n1, mC, alpha, mx); SBAR();
;   const s16x4 l6 = tr_read<v_rd_off(1, 2, 0)>(vb), h6 = tr_read<v_rd_off(1, 2, 1)>(vb);
;   asm volatile("s_waitcnt lgkmcnt(6)" ::: "memory"); SBAR();
;   o[0] = __builtin_amdgcn_mfma_f32_32x32x16_bf16(pa3, PK(l3, h3), o[0], 0, 0, 0);
;   psm_slice<3>(n0, n1, mC, alpha, mx); SBAR();
;   const s16x4 l7 = tr_read<v_rd_off(1, 3, 0)>(vb), h7 = tr_read<v_rd_off(1, 3, 1)>(vb);
;   asm volatile("s_waitcnt lgkmcnt(6)" ::: "memory"); SBAR();
;   o[1] = __builtin_amdgcn_mfma_f32_32x32x16_bf16(pa0, PK(l4, h4), o[1], 0, 0, 0);
;   psm_slice<4>(n0, n1, mC, alpha, mx); SBAR();
;   const s16x4 l8 = tr_read<v_rd_off(2, 0, 0)>(vb), h8 = tr_read<v_rd_off(2, 0, 1)>(vb);
;   asm volatile("s_waitcnt lgkmcnt(6)" ::: "memory"); SBAR();
;   o[1] = __builtin_amdgcn_mfma_f32_32x32x16_bf16(pa1, PK(l5, h5), o[1], 0, 0, 0);
;   psm_slice<5>(n0, n1, mC, alpha, mx); SBAR();
;   const s16x4 l9 = tr_read<v_rd_off(2, 1, 0)>(vb), h9 = tr_read<v_rd_off(2, 1, 1)>(vb);
;   asm volatile("s_waitcnt lgkmcnt(6)" ::: "memory"); SBAR();
;   o[1] = __builtin_amdgcn_mfma_f32_32x32x16_bf16(pa2, PK(l6, h6), o[1], 0, 0, 0);
.LBB0_495:
	ds_read_b64_tr_b16 v[178:179], v235 offset:0
	ds_read_b64_tr_b16 v[180:181], v235 offset:0x800
	ds_read_b64_tr_b16 v[182:183], v235 offset:0x1000
	ds_read_b64_tr_b16 v[184:185], v235 offset:0x1800
	ds_read_b64_tr_b16 v[186:187], v235 offset:0x2000
	ds_read_b64_tr_b16 v[188:189], v235 offset:0x2800
	ds_read_b64_tr_b16 v[192:193], v235 offset:0x3000
	ds_read_b64_tr_b16 v[194:195], v235 offset:0x3800
	s_waitcnt lgkmcnt(6)
	s_nop 0
	v_mfma_f32_32x32x16_bf16 v[50:65], v[146:149], v[178:181], v[50:65]
	ds_read_b64_tr_b16 v[178:179], v235 offset:0x200
	ds_read_b64_tr_b16 v[180:181], v235 offset:0xa00
	s_waitcnt lgkmcnt(6)
	v_mfma_f32_32x32x16_bf16 v[50:65], v[150:153], v[182:185], v[50:65]
	v_max_f32_e32 v182, v102, v102
	v_max_f32_e32 v202, v98, v182
	v_max_f32_e32 v182, v103, v103
	v_max_f32_e32 v203, v99, v182
	v_max_f32_e32 v182, v105, v105
	v_max_f32_e32 v204, v101, v182
	ds_read_b64_tr_b16 v[182:183], v235 offset:0x1200
	ds_read_b64_tr_b16 v[184:185], v235 offset:0x1a00
	s_waitcnt lgkmcnt(6)
	v_mfma_f32_32x32x16_bf16 v[50:65], v[154:157], v[186:189], v[50:65]
	v_max3_f32 v205, v100, v104, v108
	ds_read_b64_tr_b16 v[186:187], v235 offset:0x2200
	ds_read_b64_tr_b16 v[188:189], v235 offset:0x2a00
	s_waitcnt lgkmcnt(6)
	v_mfma_f32_32x32x16_bf16 v[50:65], v[158:161], v[192:195], v[50:65]
	v_max3_f32 v238, v202, v106, v110
	v_max3_f32 v246, v203, v107, v111
	v_max3_f32 v247, v204, v109, v113
	ds_read_b64_tr_b16 v[192:193], v235 offset:0x3200
	ds_read_b64_tr_b16 v[194:195], v235 offset:0x3a00
	s_waitcnt lgkmcnt(6)
	v_mfma_f32_32x32x16_bf16 v[34:49], v[146:149], v[178:181], v[34:49]
	v_max3_f32 v248, v205, v112, v84
	ds_read_b64_tr_b16 v[202:203], v235 offset:0x400
	ds_read_b64_tr_b16 v[204:205], v235 offset:0xc00
	s_waitcnt lgkmcnt(6)
	v_mfma_f32_32x32x16_bf16 v[34:49], v[150:153], v[182:185], v[34:49]
	v_max3_f32 v238, v238, v82, v86
	v_max3_f32 v246, v246, v83, v87
	v_max3_f32 v247, v247, v85, v89
	ds_read_b64_tr_b16 v[178:179], v235 offset:0x1400
	ds_read_b64_tr_b16 v[180:181], v235 offset:0x1c00
	s_waitcnt lgkmcnt(6)
	v_mfma_f32_32x32x16_bf16 v[34:49], v[154:157], v[186:189], v[34:49]
	v_max3_f32 v248, v248, v88, v92
	ds_read_b64_tr_b16 v[182:183], v235 offset:0x2400
	ds_read_b64_tr_b16 v[184:185], v235 offset:0x2c00
	s_waitcnt lgkmcnt(6)
	v_mfma_f32_32x32x16_bf16 v[34:49], v[158:161], v[192:195], v[34:49]
	v_max3_f32 v192, v238, v90, v94
	v_max3_f32 v193, v246, v91, v95
	v_max3_f32 v194, v247, v93, v97
	ds_read_b64_tr_b16 v[186:187], v235 offset:0x3400
	ds_read_b64_tr_b16 v[188:189], v235 offset:0x3c00
	s_waitcnt lgkmcnt(6)
	v_mfma_f32_32x32x16_bf16 v[18:33], v[146:149], v[202:205], v[18:33]
	v_max3_f32 v194, v248, v96, v194
	v_max3_f32 v192, v192, v193, v194
	v_cmp_ge_f32_e32 vcc, s48, v192
	s_cmp_eq_u64 vcc, exec
	v_mov_b32_e32 v238, 1.0
	s_cbranch_scc0 .LBB0_503

; template <int K>
; __device__ __forceinline__ void psm_slice(f32x16& p0, f32x16& p1, float& mC, float& alpha, float (&mx)[4]) {
;     ...
;   } else if constexpr (K == 8) {
;     float pmax = fmaxf(fmaxf(mx[0], mx[1]), fmaxf(mx[2], mx[3]));
;     { auto rr = __builtin_amdgcn_permlane32_swap(__float_as_uint(pmax), __float_as_uint(pmax), false, false);
;       pmax = fmaxf(__uint_as_float(rr[0]), __uint_as_float(rr[1])); }
;     if (__builtin_expect(__all(pmax <= THR2), 1)) { alpha = 1.f; }
;     else { const float delta = fmaxf(pmax, 0.f); alpha = __builtin_amdgcn_exp2f(-delta); mC += delta;
; #pragma unroll
;       for (int r = 0; r < 16; ++r) p0[r] -= delta;
; #pragma unroll
;       for (int r = 0; r < 16; ++r) p1[r] -= delta; }
.LBB0_502:
	v_mov_b32_e32 v193, v192
	s_nop 1
	v_permlane32_swap_b32_e32 v192, v193
	v_max_f32_e32 v244, v192, v193
	v_max_f32_e32 v192, v244, v244
	v_max_f32_e32 v192, 0, v192
	v_exp_f32_e64 v242, -v192
	v_add_f32_e32 v222, v222, v192
	v_pk_add_f32 v[98:99], v[98:99], v[192:193] op_sel_hi:[1,0] neg_lo:[0,1] neg_hi:[0,1]
	v_pk_add_f32 v[100:101], v[100:101], v[192:193] op_sel_hi:[1,0] neg_lo:[0,1] neg_hi:[0,1]
	v_pk_add_f32 v[102:103], v[102:103], v[192:193] op_sel_hi:[1,0] neg_lo:[0,1] neg_hi:[0,1]
	v_pk_add_f32 v[104:105], v[104:105], v[192:193] op_sel_hi:[1,0] neg_lo:[0,1] neg_hi:[0,1]
	v_pk_add_f32 v[106:107], v[106:107], v[192:193] op_sel_hi:[1,0] neg_lo:[0,1] neg_hi:[0,1]
	v_pk_add_f32 v[108:109], v[108:109], v[192:193] op_sel_hi:[1,0] neg_lo:[0,1] neg_hi:[0,1]
	v_pk_add_f32 v[110:111], v[110:111], v[192:193] op_sel_hi:[1,0] neg_lo:[0,1] neg_hi:[0,1]
	v_pk_add_f32 v[112:113], v[112:113], v[192:193] op_sel_hi:[1,0] neg_lo:[0,1] neg_hi:[0,1]
	v_pk_add_f32 v[82:83], v[82:83], v[192:193] op_sel_hi:[1,0] neg_lo:[0,1] neg_hi:[0,1]
	v_pk_add_f32 v[84:85], v[84:85], v[192:193] op_sel_hi:[1,0] neg_lo:[0,1] neg_hi:[0,1]
	v_pk_add_f32 v[86:87], v[86:87], v[192:193] op_sel_hi:[1,0] neg_lo:[0,1] neg_hi:[0,1]
	v_pk_add_f32 v[88:89], v[88:89], v[192:193] op_sel_hi:[1,0] neg_lo:[0,1] neg_hi:[0,1]
	v_pk_add_f32 v[90:91], v[90:91], v[192:193] op_sel_hi:[1,0] neg_lo:[0,1] neg_hi:[0,1]
	v_pk_add_f32 v[92:93], v[92:93], v[192:193] op_sel_hi:[1,0] neg_lo:[0,1] neg_hi:[0,1]
	v_pk_add_f32 v[94:95], v[94:95], v[192:193] op_sel_hi:[1,0] neg_lo:[0,1] neg_hi:[0,1]
	v_pk_add_f32 v[96:97], v[96:97], v[192:193] op_sel_hi:[1,0] neg_lo:[0,1] neg_hi:[0,1]
	s_branch .LBB0_489
.LBB0_503:
	v_mov_b32_e32 v193, v192
	s_nop 1
	v_permlane32_swap_b32_e32 v192, v193
	v_max_f32_e32 v246, v192, v193
	v_max_f32_e32 v192, v246, v246
	v_max_f32_e32 v192, 0, v192
	v_exp_f32_e64 v238, -v192
	v_add_f32_e32 v222, v222, v192
	v_pk_add_f32 v[98:99], v[98:99], v[192:193] op_sel_hi:[1,0] neg_lo:[0,1] neg_hi:[0,1]
	v_pk_add_f32 v[100:101], v[100:101], v[192:193] op_sel_hi:[1,0] neg_lo:[0,1] neg_hi:[0,1]
	v_pk_add_f32 v[102:103], v[102:103], v[192:193] op_sel_hi:[1,0] neg_lo:[0,1] neg_hi:[0,1]
	v_pk_add_f32 v[104:105], v[104:105], v[192:193] op_sel_hi:[1,0] neg_lo:[0,1] neg_hi:[0,1]
	v_pk_add_f32 v[106:107], v[106:107], v[192:193] op_sel_hi:[1,0] neg_lo:[0,1] neg_hi:[0,1]
	v_pk_add_f32 v[108:109], v[108:109], v[192:193] op_sel_hi:[1,0] neg_lo:[0,1] neg_hi:[0,1]
	v_pk_add_f32 v[110:111], v[110:111], v[192:193] op_sel_hi:[1,0] neg_lo:[0,1] neg_hi:[0,1]
	v_pk_add_f32 v[112:113], v[112:113], v[192:193] op_sel_hi:[1,0] neg_lo:[0,1] neg_hi:[0,1]
	v_pk_add_f32 v[82:83], v[82:83], v[192:193] op_sel_hi:[1,0] neg_lo:[0,1] neg_hi:[0,1]
	v_pk_add_f32 v[84:85], v[84:85], v[192:193] op_sel_hi:[1,0] neg_lo:[0,1] neg_hi:[0,1]
	v_pk_add_f32 v[86:87], v[86:87], v[192:193] op_sel_hi:[1,0] neg_lo:[0,1] neg_hi:[0,1]
	v_pk_add_f32 v[88:89], v[88:89], v[192:193] op_sel_hi:[1,0] neg_lo:[0,1] neg_hi:[0,1]
	v_pk_add_f32 v[90:91], v[90:91], v[192:193] op_sel_hi:[1,0] neg_lo:[0,1] neg_hi:[0,1]
	v_pk_add_f32 v[92:93], v[92:93], v[192:193] op_sel_hi:[1,0] neg_lo:[0,1] neg_hi:[0,1]
	v_pk_add_f32 v[94:95], v[94:95], v[192:193] op_sel_hi:[1,0] neg_lo:[0,1] neg_hi:[0,1]
	v_pk_add_f32 v[96:97], v[96:97], v[192:193] op_sel_hi:[1,0] neg_lo:[0,1] neg_hi:[0,1]
	s_branch .LBB0_496
